# P5 mixer-out: GLA epilogue gate/gain loads prefetched; GLA q.S and K.Q/P.V loops and SSD C.h_enter section software-pipelined with register pools; SSD head epilogue loads batched; hipcc regions kept a
# speedup vs baseline: 1.0407x; 1.0407x over previous
.Lp4_done:
	s_nop 0
	s_nop 0
	s_nop 0
	s_nop 0
	s_nop 0
	s_nop 0
	s_nop 0
	s_nop 0
	s_nop 0
	s_nop 0

.LBB0_899:
	s_or_b64 exec, exec, s[0:1]
	s_lshl_b32 s0, s84, 5
	v_bitop3_b32 v83, v120, 32, s0 bitop3:0x36
	v_lshl_add_u32 v83, v83, 2, v225
	s_waitcnt lgkmcnt(0)
	s_barrier
	ds_read_b128 v[84:87], v83
	ds_read_b128 v[98:101], v83 offset:16
	ds_read_b128 v[102:105], v83 offset:32
	ds_read_b128 v[106:109], v83 offset:48
	s_mov_b32 s0, 0x3727c5ac
	s_waitcnt lgkmcnt(3)
	v_pk_add_f32 v[66:67], v[66:67], v[84:85]
	v_mov_b64_e32 v[110:111], s[0:1]
	v_pk_fma_f32 v[66:67], v[66:67], s[92:93], v[110:111] op_sel_hi:[1,0,0]
	s_nop 0
	v_mul_f32_e32 v83, 0x4b800000, v66
	v_cmp_gt_f32_e64 s[0:1], s83, v66
	v_cmp_gt_f32_e32 vcc, s83, v67
	s_nop 0
	v_cndmask_b32_e64 v66, v66, v83, s[0:1]
	v_rsq_f32_e32 v66, v66
	s_nop 0
	v_mul_f32_e32 v83, 0x45800000, v66
	v_cndmask_b32_e64 v94, v66, v83, s[0:1]
	v_mul_f32_e32 v66, 0x4b800000, v67
	v_cndmask_b32_e32 v66, v67, v66, vcc
	v_rsq_f32_e32 v66, v66
	v_mul_f32_e32 v50, v50, v94
	v_mul_f32_e32 v34, v34, v94
	v_mul_f32_e32 v18, v18, v94
	v_mul_f32_e32 v67, 0x45800000, v66
	v_cndmask_b32_e32 v96, v66, v67, vcc
	v_pk_add_f32 v[66:67], v[68:69], v[86:87]
	v_mul_f32_e32 v51, v51, v96
	v_pk_fma_f32 v[66:67], v[66:67], s[92:93], v[110:111] op_sel_hi:[1,0,0]
	v_mul_f32_e32 v35, v35, v96
	v_mul_f32_e32 v68, 0x4b800000, v66
	v_cmp_gt_f32_e64 s[0:1], s83, v66
	v_cmp_gt_f32_e32 vcc, s83, v67
	v_mul_f32_e32 v19, v19, v96
	v_cndmask_b32_e64 v66, v66, v68, s[0:1]
	v_rsq_f32_e32 v66, v66
	v_mul_f32_e32 v2, v2, v94
	v_mul_f32_e32 v3, v3, v96
	v_mul_f32_e32 v68, 0x45800000, v66
	v_cndmask_b32_e64 v93, v66, v68, s[0:1]
	v_mul_f32_e32 v66, 0x4b800000, v67
	v_cndmask_b32_e32 v66, v67, v66, vcc
	v_rsq_f32_e32 v66, v66
	s_nop 0
	v_mul_f32_e32 v67, 0x45800000, v66
	v_cndmask_b32_e32 v95, v66, v67, vcc
	s_waitcnt lgkmcnt(2)
	v_pk_add_f32 v[66:67], v[70:71], v[98:99]
	s_nop 0
	v_pk_fma_f32 v[66:67], v[66:67], s[92:93], v[110:111] op_sel_hi:[1,0,0]
	s_nop 0
	v_mul_f32_e32 v68, 0x4b800000, v66
	v_cmp_gt_f32_e64 s[0:1], s83, v66
	v_cmp_gt_f32_e32 vcc, s83, v67
	s_nop 0
	v_cndmask_b32_e64 v66, v66, v68, s[0:1]
	v_rsq_f32_e32 v66, v66
	s_nop 0
	v_mul_f32_e32 v68, 0x45800000, v66
	v_cndmask_b32_e64 v91, v66, v68, s[0:1]
	v_mul_f32_e32 v66, 0x4b800000, v67
	v_cndmask_b32_e32 v66, v67, v66, vcc
	v_rsq_f32_e32 v66, v66
	s_nop 0
	v_mul_f32_e32 v67, 0x45800000, v66
	v_cndmask_b32_e32 v92, v66, v67, vcc
	v_pk_add_f32 v[66:67], v[72:73], v[100:101]
	s_nop 0
	v_pk_fma_f32 v[66:67], v[66:67], s[92:93], v[110:111] op_sel_hi:[1,0,0]
	s_nop 0
	v_mul_f32_e32 v68, 0x4b800000, v66
	v_cmp_gt_f32_e64 s[0:1], s83, v66
	v_cmp_gt_f32_e32 vcc, s83, v67
	s_nop 0
	v_cndmask_b32_e64 v66, v66, v68, s[0:1]
	v_rsq_f32_e32 v66, v66
	s_nop 0
	v_mul_f32_e32 v68, 0x45800000, v66
	v_cndmask_b32_e64 v89, v66, v68, s[0:1]
	v_mul_f32_e32 v66, 0x4b800000, v67
	v_cndmask_b32_e32 v66, v67, v66, vcc
	v_rsq_f32_e32 v66, v66
	s_nop 0
	v_mul_f32_e32 v67, 0x45800000, v66
	v_cndmask_b32_e32 v90, v66, v67, vcc
	s_waitcnt lgkmcnt(1)
	v_pk_add_f32 v[66:67], v[74:75], v[102:103]
	s_nop 0
	v_pk_fma_f32 v[66:67], v[66:67], s[92:93], v[110:111] op_sel_hi:[1,0,0]
	s_nop 0
	v_mul_f32_e32 v68, 0x4b800000, v66
	v_cmp_gt_f32_e64 s[0:1], s83, v66
	v_cmp_gt_f32_e32 vcc, s83, v67
	s_nop 0
	v_cndmask_b32_e64 v66, v66, v68, s[0:1]
	v_rsq_f32_e32 v66, v66
	s_nop 0
	v_mul_f32_e32 v68, 0x45800000, v66
	v_cndmask_b32_e64 v87, v66, v68, s[0:1]
	v_mul_f32_e32 v66, 0x4b800000, v67
	v_cndmask_b32_e32 v66, v67, v66, vcc
	v_rsq_f32_e32 v66, v66
	s_nop 0
	v_mul_f32_e32 v67, 0x45800000, v66
	v_cndmask_b32_e32 v88, v66, v67, vcc
	v_pk_add_f32 v[66:67], v[76:77], v[104:105]
	s_nop 0
	v_pk_fma_f32 v[66:67], v[66:67], s[92:93], v[110:111] op_sel_hi:[1,0,0]
	s_nop 0
	v_mul_f32_e32 v68, 0x4b800000, v66
	v_cmp_gt_f32_e64 s[0:1], s83, v66
	v_cmp_gt_f32_e32 vcc, s83, v67
	s_nop 0
	v_cndmask_b32_e64 v66, v66, v68, s[0:1]
	v_rsq_f32_e32 v66, v66
	s_nop 0
	v_mul_f32_e32 v68, 0x45800000, v66
	v_cndmask_b32_e64 v85, v66, v68, s[0:1]
	v_mul_f32_e32 v66, 0x4b800000, v67
	v_cndmask_b32_e32 v66, v67, v66, vcc
	v_rsq_f32_e32 v66, v66
	s_nop 0
	v_mul_f32_e32 v67, 0x45800000, v66
	v_cndmask_b32_e32 v86, v66, v67, vcc
	s_waitcnt lgkmcnt(0)
	v_pk_add_f32 v[66:67], v[78:79], v[106:107]
	s_nop 0
	v_pk_fma_f32 v[66:67], v[66:67], s[92:93], v[110:111] op_sel_hi:[1,0,0]
	s_nop 0
	v_mul_f32_e32 v68, 0x4b800000, v66
	v_cmp_gt_f32_e64 s[0:1], s83, v66
	v_cmp_gt_f32_e32 vcc, s83, v67
	s_nop 0
	v_cndmask_b32_e64 v66, v66, v68, s[0:1]
	v_rsq_f32_e32 v66, v66
	s_nop 0
	v_mul_f32_e32 v68, 0x45800000, v66
	v_cndmask_b32_e64 v83, v66, v68, s[0:1]
	v_mul_f32_e32 v66, 0x4b800000, v67
	v_cndmask_b32_e32 v66, v67, v66, vcc
	v_rsq_f32_e32 v66, v66
	s_nop 0
	v_mul_f32_e32 v67, 0x45800000, v66
	v_cndmask_b32_e32 v84, v66, v67, vcc
	v_pk_add_f32 v[66:67], v[80:81], v[108:109]
	s_nop 0
	v_pk_fma_f32 v[66:67], v[66:67], s[92:93], v[110:111] op_sel_hi:[1,0,0]
	s_nop 0
	v_mul_f32_e32 v68, 0x4b800000, v66
	v_cmp_gt_f32_e64 s[0:1], s83, v66
	v_cmp_gt_f32_e32 vcc, s83, v67
	s_nop 0
	v_cndmask_b32_e64 v66, v66, v68, s[0:1]
	v_rsq_f32_e32 v66, v66
	s_nop 0
	v_mul_f32_e32 v68, 0x45800000, v66
	v_cndmask_b32_e64 v78, v66, v68, s[0:1]
	v_mul_f32_e32 v66, 0x4b800000, v67
	v_cndmask_b32_e32 v66, v67, v66, vcc
	v_rsq_f32_e32 v66, v66
	v_readlane_b32 s0, v253, 0
	v_readlane_b32 s4, v253, 4
	v_readlane_b32 s5, v253, 5
	v_mul_f32_e32 v67, 0x45800000, v66
	v_cndmask_b32_e32 v79, v66, v67, vcc
	v_lshl_or_b32 v67, s85, 7, v118
	v_or_b32_e32 v80, v67, v231
	v_lshlrev_b32_e32 v81, 2, v80
	v_and_b32_e32 v66, 1, v116
	s_movk_i32 s0, 0x39e
	v_cmp_eq_u32_e32 vcc, 0, v66
	v_or3_b32 v74, v117, v119, v66
	v_bitop3_b32 v66, v67, s0, v231 bitop3:0xc8
	v_lshlrev_b32_e32 v114, 1, v66
	v_ashrrev_i32_e32 v75, 31, v74
	v_lshl_add_u64 v[76:77], s[80:81], 0, v[114:115]
	v_lshlrev_b64 v[72:73], 11, v[74:75]
	v_lshl_add_u64 v[170:171], v[76:77], 0, v[72:73]
	v_or_b32_e32 v186, 2, v74
	v_ashrrev_i32_e32 v187, 31, v186
	v_lshlrev_b64 v[186:187], 11, v[186:187]
	v_lshl_add_u64 v[172:173], v[76:77], 0, v[186:187]
	v_or_b32_e32 v186, 8, v74
	v_ashrrev_i32_e32 v187, 31, v186
	v_lshlrev_b64 v[186:187], 11, v[186:187]
	v_lshl_add_u64 v[174:175], v[76:77], 0, v[186:187]
	v_or_b32_e32 v186, 10, v74
	v_ashrrev_i32_e32 v187, 31, v186
	v_lshlrev_b64 v[186:187], 11, v[186:187]
	v_lshl_add_u64 v[176:177], v[76:77], 0, v[186:187]
	v_or_b32_e32 v186, 16, v74
	v_ashrrev_i32_e32 v187, 31, v186
	v_lshlrev_b64 v[186:187], 11, v[186:187]
	v_lshl_add_u64 v[178:179], v[76:77], 0, v[186:187]
	v_or_b32_e32 v186, 18, v74
	v_ashrrev_i32_e32 v187, 31, v186
	v_lshlrev_b64 v[186:187], 11, v[186:187]
	v_lshl_add_u64 v[180:181], v[76:77], 0, v[186:187]
	v_or_b32_e32 v186, 24, v74
	v_ashrrev_i32_e32 v187, 31, v186
	v_lshlrev_b64 v[186:187], 11, v[186:187]
	v_lshl_add_u64 v[182:183], v[76:77], 0, v[186:187]
	v_or_b32_e32 v186, 26, v74
	v_ashrrev_i32_e32 v187, 31, v186
	v_lshlrev_b64 v[186:187], 11, v[186:187]
	v_lshl_add_u64 v[184:185], v[76:77], 0, v[186:187]
	global_load_dword v97, v81, s[4:5]
	global_load_dword v167, v81, s[4:5] offset:128
	global_load_dword v168, v81, s[4:5] offset:256
	global_load_dword v169, v81, s[4:5] offset:384
	global_load_dword v134, v[170:171], off
	global_load_dword v135, v[172:173], off
	global_load_dword v136, v[174:175], off
	global_load_dword v137, v[176:177], off
	global_load_dword v138, v[178:179], off
	global_load_dword v139, v[180:181], off
	global_load_dword v140, v[182:183], off
	global_load_dword v141, v[184:185], off
	global_load_dword v142, v[170:171], off offset:64
	global_load_dword v143, v[172:173], off offset:64
	global_load_dword v144, v[174:175], off offset:64
	global_load_dword v145, v[176:177], off offset:64
	global_load_dword v146, v[178:179], off offset:64
	global_load_dword v147, v[180:181], off offset:64
	global_load_dword v148, v[182:183], off offset:64
	global_load_dword v149, v[184:185], off offset:64
	global_load_dword v150, v[170:171], off offset:128
	global_load_dword v151, v[172:173], off offset:128
	global_load_dword v152, v[174:175], off offset:128
	global_load_dword v153, v[176:177], off offset:128
	global_load_dword v154, v[178:179], off offset:128
	global_load_dword v155, v[180:181], off offset:128
	global_load_dword v156, v[182:183], off offset:128
	global_load_dword v157, v[184:185], off offset:128
	global_load_dword v158, v[170:171], off offset:192
	global_load_dword v159, v[172:173], off offset:192
	global_load_dword v160, v[174:175], off offset:192
	global_load_dword v161, v[176:177], off offset:192
	global_load_dword v162, v[178:179], off offset:192
	global_load_dword v163, v[180:181], off offset:192
	global_load_dword v164, v[182:183], off offset:192
	global_load_dword v165, v[184:185], off offset:192
	s_waitcnt vmcnt(0)
	s_movk_i32 s0, 0x3be
	v_readlane_b32 s1, v253, 1
	v_readlane_b32 s2, v253, 2
	v_readlane_b32 s3, v253, 3
	v_readlane_b32 s6, v253, 6
	v_readlane_b32 s7, v253, 7
	v_readlane_b32 s8, v253, 8
	v_readlane_b32 s9, v253, 9
	v_readlane_b32 s10, v253, 10
	v_readlane_b32 s11, v253, 11
	v_readlane_b32 s12, v253, 12
	v_readlane_b32 s13, v253, 13
	v_readlane_b32 s14, v253, 14
	v_readlane_b32 s15, v253, 15
	v_mul_f32_e32 v50, v50, v97
	v_mul_f32_e32 v51, v51, v97
	v_cndmask_b32_e32 v66, v50, v51, vcc
	ds_bpermute_b32 v66, v82, v66
	s_waitcnt lgkmcnt(0)
	v_cndmask_b32_e32 v67, v66, v50, vcc
	v_cndmask_b32_e32 v66, v51, v66, vcc
	v_lshl_add_u64 v[50:51], v[76:77], 0, v[72:73]
	v_mov_b32_e32 v68, v134
	v_lshlrev_b32_e32 v69, 16, v68
	v_mul_f32_e32 v70, 0xbfb8aa3b, v69
	v_exp_f32_e32 v70, v70
	v_and_b32_e32 v68, 0xffff0000, v68
	v_add_f32_e32 v70, 1.0, v70
	v_rcp_f32_e32 v70, v70
	s_nop 0
	v_mul_f32_e32 v69, v70, v69
	v_mul_f32_e32 v67, v67, v69
	v_mul_f32_e32 v69, 0xbfb8aa3b, v68
	v_exp_f32_e32 v69, v69
	s_nop 0
	v_add_f32_e32 v69, 1.0, v69
	v_rcp_f32_e32 v69, v69
	s_nop 0
	v_mul_f32_e32 v68, v69, v68
	v_mul_f32_e32 v66, v66, v68
	v_cvt_pk_bf16_f32 v66, v67, v66
	global_store_dword v[50:51], v66, off
	v_mul_f32_e32 v50, v52, v93
	v_mul_f32_e32 v51, v53, v95
	v_mul_f32_e32 v50, v50, v97
	v_mul_f32_e32 v51, v51, v97
	v_cndmask_b32_e32 v52, v50, v51, vcc
	ds_bpermute_b32 v52, v82, v52
	s_waitcnt lgkmcnt(0)
	v_cndmask_b32_e32 v53, v52, v50, vcc
	v_or_b32_e32 v50, 2, v74
	v_cndmask_b32_e32 v52, v51, v52, vcc
	v_ashrrev_i32_e32 v51, 31, v50
	v_lshlrev_b64 v[70:71], 11, v[50:51]
	v_lshl_add_u64 v[50:51], v[76:77], 0, v[70:71]
	v_mov_b32_e32 v66, v135
	v_lshlrev_b32_e32 v67, 16, v66
	v_mul_f32_e32 v68, 0xbfb8aa3b, v67
	v_exp_f32_e32 v68, v68
	v_and_b32_e32 v66, 0xffff0000, v66
	v_add_f32_e32 v68, 1.0, v68
	v_rcp_f32_e32 v68, v68
	s_nop 0
	v_mul_f32_e32 v67, v68, v67
	v_mul_f32_e32 v53, v53, v67
	v_mul_f32_e32 v67, 0xbfb8aa3b, v66
	v_exp_f32_e32 v67, v67
	s_nop 0
	v_add_f32_e32 v67, 1.0, v67
	v_rcp_f32_e32 v67, v67
	s_nop 0
	v_mul_f32_e32 v66, v67, v66
	v_mul_f32_e32 v52, v52, v66
	v_cvt_pk_bf16_f32 v52, v53, v52
	global_store_dword v[50:51], v52, off
	v_mul_f32_e32 v50, v54, v91
	v_mul_f32_e32 v51, v55, v92
	v_mul_f32_e32 v50, v50, v97
	v_mul_f32_e32 v51, v51, v97
	v_cndmask_b32_e32 v52, v50, v51, vcc
	ds_bpermute_b32 v52, v82, v52
	s_waitcnt lgkmcnt(0)
	v_cndmask_b32_e32 v53, v52, v50, vcc
	v_or_b32_e32 v50, 8, v74
	v_cndmask_b32_e32 v52, v51, v52, vcc
	v_ashrrev_i32_e32 v51, 31, v50
	v_lshlrev_b64 v[68:69], 11, v[50:51]
	v_lshl_add_u64 v[50:51], v[76:77], 0, v[68:69]
	v_mov_b32_e32 v54, v136
	v_lshlrev_b32_e32 v55, 16, v54
	v_mul_f32_e32 v66, 0xbfb8aa3b, v55
	v_exp_f32_e32 v66, v66
	v_and_b32_e32 v54, 0xffff0000, v54
	v_add_f32_e32 v66, 1.0, v66
	v_rcp_f32_e32 v66, v66
	s_nop 0
	v_mul_f32_e32 v55, v66, v55
	v_mul_f32_e32 v53, v53, v55
	v_mul_f32_e32 v55, 0xbfb8aa3b, v54
	v_exp_f32_e32 v55, v55
	s_nop 0
	v_add_f32_e32 v55, 1.0, v55
	v_rcp_f32_e32 v55, v55
	s_nop 0
	v_mul_f32_e32 v54, v55, v54
	v_mul_f32_e32 v52, v52, v54
	v_cvt_pk_bf16_f32 v52, v53, v52
	global_store_dword v[50:51], v52, off
	v_mul_f32_e32 v50, v56, v89
	v_mul_f32_e32 v51, v57, v90
	v_mul_f32_e32 v50, v97, v50
	v_mul_f32_e32 v51, v97, v51
	v_cndmask_b32_e32 v52, v50, v51, vcc
	ds_bpermute_b32 v52, v82, v52
	s_waitcnt lgkmcnt(0)
	v_cndmask_b32_e32 v53, v52, v50, vcc
	v_or_b32_e32 v50, 10, v74
	v_cndmask_b32_e32 v52, v51, v52, vcc
	v_ashrrev_i32_e32 v51, 31, v50
	v_lshlrev_b64 v[66:67], 11, v[50:51]
	v_lshl_add_u64 v[50:51], v[76:77], 0, v[66:67]
	v_mov_b32_e32 v54, v137
	v_lshlrev_b32_e32 v55, 16, v54
	v_mul_f32_e32 v56, 0xbfb8aa3b, v55
	v_exp_f32_e32 v56, v56
	v_and_b32_e32 v54, 0xffff0000, v54
	v_add_f32_e32 v56, 1.0, v56
	v_rcp_f32_e32 v56, v56
	s_nop 0
	v_mul_f32_e32 v55, v56, v55
	v_mul_f32_e32 v53, v53, v55
	v_mul_f32_e32 v55, 0xbfb8aa3b, v54
	v_exp_f32_e32 v55, v55
	s_nop 0
	v_add_f32_e32 v55, 1.0, v55
	v_rcp_f32_e32 v55, v55
	s_nop 0
	v_mul_f32_e32 v54, v55, v54
	v_mul_f32_e32 v52, v52, v54
	v_cvt_pk_bf16_f32 v52, v53, v52
	global_store_dword v[50:51], v52, off
	v_mul_f32_e32 v50, v58, v87
	v_mul_f32_e32 v51, v59, v88
	v_mul_f32_e32 v50, v97, v50
	v_mul_f32_e32 v51, v97, v51
	v_cndmask_b32_e32 v52, v50, v51, vcc
	ds_bpermute_b32 v52, v82, v52
	s_waitcnt lgkmcnt(0)
	v_cndmask_b32_e32 v53, v52, v50, vcc
	v_or_b32_e32 v50, 16, v74
	v_cndmask_b32_e32 v52, v51, v52, vcc
	v_ashrrev_i32_e32 v51, 31, v50
	v_lshlrev_b64 v[56:57], 11, v[50:51]
	v_lshl_add_u64 v[50:51], v[76:77], 0, v[56:57]
	v_mov_b32_e32 v54, v138
	v_lshlrev_b32_e32 v55, 16, v54
	v_mul_f32_e32 v58, 0xbfb8aa3b, v55
	v_exp_f32_e32 v58, v58
	v_and_b32_e32 v54, 0xffff0000, v54
	v_add_f32_e32 v58, 1.0, v58
	v_rcp_f32_e32 v58, v58
	s_nop 0
	v_mul_f32_e32 v55, v58, v55
	v_mul_f32_e32 v53, v53, v55
	v_mul_f32_e32 v55, 0xbfb8aa3b, v54
	v_exp_f32_e32 v55, v55
	s_nop 0
	v_add_f32_e32 v55, 1.0, v55
	v_rcp_f32_e32 v55, v55
	s_nop 0
	v_mul_f32_e32 v54, v55, v54
	v_mul_f32_e32 v52, v52, v54
	v_cvt_pk_bf16_f32 v52, v53, v52
	global_store_dword v[50:51], v52, off
	v_mul_f32_e32 v50, v60, v85
	v_mul_f32_e32 v51, v61, v86
	v_mul_f32_e32 v50, v97, v50
	v_mul_f32_e32 v51, v97, v51
	v_cndmask_b32_e32 v52, v50, v51, vcc
	ds_bpermute_b32 v52, v82, v52
	s_waitcnt lgkmcnt(0)
	v_cndmask_b32_e32 v53, v52, v50, vcc
	v_or_b32_e32 v50, 18, v74
	v_cndmask_b32_e32 v52, v51, v52, vcc
	v_ashrrev_i32_e32 v51, 31, v50
	v_lshlrev_b64 v[54:55], 11, v[50:51]
	v_lshl_add_u64 v[50:51], v[76:77], 0, v[54:55]
	v_mov_b32_e32 v58, v139
	v_lshlrev_b32_e32 v59, 16, v58
	v_mul_f32_e32 v60, 0xbfb8aa3b, v59
	v_exp_f32_e32 v60, v60
	v_and_b32_e32 v58, 0xffff0000, v58
	v_add_f32_e32 v60, 1.0, v60
	v_rcp_f32_e32 v60, v60
	s_nop 0
	v_mul_f32_e32 v59, v60, v59
	v_mul_f32_e32 v53, v53, v59
	v_mul_f32_e32 v59, 0xbfb8aa3b, v58
	v_exp_f32_e32 v59, v59
	s_nop 0
	v_add_f32_e32 v59, 1.0, v59
	v_rcp_f32_e32 v59, v59
	s_nop 0
	v_mul_f32_e32 v58, v59, v58
	v_mul_f32_e32 v52, v52, v58
	v_cvt_pk_bf16_f32 v52, v53, v52
	global_store_dword v[50:51], v52, off
	v_mul_f32_e32 v50, v62, v83
	v_mul_f32_e32 v51, v63, v84
	v_mul_f32_e32 v50, v97, v50
	v_mul_f32_e32 v51, v97, v51
	v_cndmask_b32_e32 v52, v50, v51, vcc
	ds_bpermute_b32 v52, v82, v52
	s_waitcnt lgkmcnt(0)
	v_cndmask_b32_e32 v58, v52, v50, vcc
	v_or_b32_e32 v50, 24, v74
	v_cndmask_b32_e32 v59, v51, v52, vcc
	v_ashrrev_i32_e32 v51, 31, v50
	v_lshlrev_b64 v[52:53], 11, v[50:51]
	v_lshl_add_u64 v[50:51], v[76:77], 0, v[52:53]
	v_mov_b32_e32 v60, v140
	v_lshlrev_b32_e32 v61, 16, v60
	v_mul_f32_e32 v62, 0xbfb8aa3b, v61
	v_exp_f32_e32 v62, v62
	v_and_b32_e32 v60, 0xffff0000, v60
	v_add_f32_e32 v62, 1.0, v62
	v_rcp_f32_e32 v62, v62
	s_nop 0
	v_mul_f32_e32 v61, v62, v61
	v_mul_f32_e32 v58, v58, v61
	v_mul_f32_e32 v61, 0xbfb8aa3b, v60
	v_exp_f32_e32 v61, v61
	s_nop 0
	v_add_f32_e32 v61, 1.0, v61
	v_rcp_f32_e32 v61, v61
	s_nop 0
	v_mul_f32_e32 v60, v61, v60
	v_mul_f32_e32 v59, v59, v60
	v_cvt_pk_bf16_f32 v58, v58, v59
	global_store_dword v[50:51], v58, off
	v_mul_f32_e32 v50, v64, v78
	v_mul_f32_e32 v51, v65, v79
	v_mul_f32_e32 v50, v97, v50
	v_mul_f32_e32 v51, v97, v51
	v_cndmask_b32_e32 v58, v50, v51, vcc
	ds_bpermute_b32 v58, v82, v58
	s_waitcnt lgkmcnt(0)
	v_cndmask_b32_e32 v60, v58, v50, vcc
	v_or_b32_e32 v50, 26, v74
	v_cndmask_b32_e32 v61, v51, v58, vcc
	v_ashrrev_i32_e32 v51, 31, v50
	v_lshlrev_b64 v[50:51], 11, v[50:51]
	v_lshl_add_u64 v[58:59], v[76:77], 0, v[50:51]
	v_mov_b32_e32 v62, v141
	v_lshlrev_b32_e32 v63, 16, v62
	v_mul_f32_e32 v64, 0xbfb8aa3b, v63
	v_exp_f32_e32 v64, v64
	v_and_b32_e32 v62, 0xffff0000, v62
	v_add_f32_e32 v64, 1.0, v64
	v_rcp_f32_e32 v64, v64
	s_nop 0
	v_mul_f32_e32 v63, v64, v63
	v_mul_f32_e32 v60, v60, v63
	v_mul_f32_e32 v63, 0xbfb8aa3b, v62
	v_exp_f32_e32 v63, v63
	s_nop 0
	v_add_f32_e32 v63, 1.0, v63
	v_rcp_f32_e32 v63, v63
	s_nop 0
	v_mul_f32_e32 v62, v63, v62
	v_mul_f32_e32 v61, v61, v62
	v_cvt_pk_bf16_f32 v60, v60, v61
	global_store_dword v[58:59], v60, off
	v_mov_b32_e32 v60, v167
	v_bitop3_b32 v58, v80, s0, 32 bitop3:0xc8
	v_lshlrev_b32_e32 v114, 1, v58
	v_lshl_add_u64 v[58:59], s[80:81], 0, v[114:115]
	s_movk_i32 s0, 0x3de
	v_mul_f32_e32 v34, v34, v60
	v_mul_f32_e32 v35, v35, v60
	v_cndmask_b32_e32 v61, v34, v35, vcc
	ds_bpermute_b32 v61, v82, v61
	s_waitcnt lgkmcnt(0)
	v_cndmask_b32_e32 v62, v61, v34, vcc
	v_cndmask_b32_e32 v61, v35, v61, vcc
	v_lshl_add_u64 v[34:35], v[58:59], 0, v[72:73]
	v_mov_b32_e32 v63, v142
	v_lshlrev_b32_e32 v64, 16, v63
	v_mul_f32_e32 v65, 0xbfb8aa3b, v64
	v_exp_f32_e32 v65, v65
	v_and_b32_e32 v63, 0xffff0000, v63
	v_add_f32_e32 v65, 1.0, v65
	v_rcp_f32_e32 v65, v65
	s_nop 0
	v_mul_f32_e32 v64, v65, v64
	v_mul_f32_e32 v62, v62, v64
	v_mul_f32_e32 v64, 0xbfb8aa3b, v63
	v_exp_f32_e32 v64, v64
	s_nop 0
	v_add_f32_e32 v64, 1.0, v64
	v_rcp_f32_e32 v64, v64
	s_nop 0
	v_mul_f32_e32 v63, v64, v63
	v_mul_f32_e32 v61, v61, v63
	v_cvt_pk_bf16_f32 v61, v62, v61
	global_store_dword v[34:35], v61, off
	v_mul_f32_e32 v34, v36, v93
	v_mul_f32_e32 v35, v37, v95
	v_mul_f32_e32 v34, v34, v60
	v_mul_f32_e32 v35, v35, v60
	v_cndmask_b32_e32 v36, v34, v35, vcc
	ds_bpermute_b32 v36, v82, v36
	s_waitcnt lgkmcnt(0)
	v_cndmask_b32_e32 v37, v36, v34, vcc
	v_cndmask_b32_e32 v36, v35, v36, vcc
	v_lshl_add_u64 v[34:35], v[58:59], 0, v[70:71]
	v_mov_b32_e32 v61, v143
	v_lshlrev_b32_e32 v62, 16, v61
	v_mul_f32_e32 v63, 0xbfb8aa3b, v62
	v_exp_f32_e32 v63, v63
	v_and_b32_e32 v61, 0xffff0000, v61
	v_add_f32_e32 v63, 1.0, v63
	v_rcp_f32_e32 v63, v63
	s_nop 0
	v_mul_f32_e32 v62, v63, v62
	v_mul_f32_e32 v37, v37, v62
	v_mul_f32_e32 v62, 0xbfb8aa3b, v61
	v_exp_f32_e32 v62, v62
	s_nop 0
	v_add_f32_e32 v62, 1.0, v62
	v_rcp_f32_e32 v62, v62
	s_nop 0
	v_mul_f32_e32 v61, v62, v61
	v_mul_f32_e32 v36, v36, v61
	v_cvt_pk_bf16_f32 v36, v37, v36
	global_store_dword v[34:35], v36, off
	v_mul_f32_e32 v34, v38, v91
	v_mul_f32_e32 v35, v39, v92
	v_mul_f32_e32 v34, v34, v60
	v_mul_f32_e32 v35, v35, v60
	v_cndmask_b32_e32 v36, v34, v35, vcc
	ds_bpermute_b32 v36, v82, v36
	s_waitcnt lgkmcnt(0)
	v_cndmask_b32_e32 v37, v36, v34, vcc
	v_cndmask_b32_e32 v36, v35, v36, vcc
	v_lshl_add_u64 v[34:35], v[58:59], 0, v[68:69]
	v_mov_b32_e32 v38, v144
	v_lshlrev_b32_e32 v39, 16, v38
	v_mul_f32_e32 v61, 0xbfb8aa3b, v39
	v_exp_f32_e32 v61, v61
	v_and_b32_e32 v38, 0xffff0000, v38
	v_add_f32_e32 v61, 1.0, v61
	v_rcp_f32_e32 v61, v61
	s_nop 0
	v_mul_f32_e32 v39, v61, v39
	v_mul_f32_e32 v37, v37, v39
	v_mul_f32_e32 v39, 0xbfb8aa3b, v38
	v_exp_f32_e32 v39, v39
	s_nop 0
	v_add_f32_e32 v39, 1.0, v39
	v_rcp_f32_e32 v39, v39
	s_nop 0
	v_mul_f32_e32 v38, v39, v38
	v_mul_f32_e32 v36, v36, v38
	v_cvt_pk_bf16_f32 v36, v37, v36
	global_store_dword v[34:35], v36, off
	v_mul_f32_e32 v34, v40, v89
	v_mul_f32_e32 v35, v41, v90
	v_mul_f32_e32 v34, v34, v60
	v_mul_f32_e32 v35, v35, v60
	v_cndmask_b32_e32 v36, v34, v35, vcc
	ds_bpermute_b32 v36, v82, v36
	s_waitcnt lgkmcnt(0)
	v_cndmask_b32_e32 v37, v36, v34, vcc
	v_cndmask_b32_e32 v36, v35, v36, vcc
	v_lshl_add_u64 v[34:35], v[58:59], 0, v[66:67]
	v_mov_b32_e32 v38, v145
	v_lshlrev_b32_e32 v39, 16, v38
	v_mul_f32_e32 v40, 0xbfb8aa3b, v39
	v_exp_f32_e32 v40, v40
	v_and_b32_e32 v38, 0xffff0000, v38
	v_add_f32_e32 v40, 1.0, v40
	v_rcp_f32_e32 v40, v40
	s_nop 0
	v_mul_f32_e32 v39, v40, v39
	v_mul_f32_e32 v37, v37, v39
	v_mul_f32_e32 v39, 0xbfb8aa3b, v38
	v_exp_f32_e32 v39, v39
	s_nop 0
	v_add_f32_e32 v39, 1.0, v39
	v_rcp_f32_e32 v39, v39
	s_nop 0
	v_mul_f32_e32 v38, v39, v38
	v_mul_f32_e32 v36, v36, v38
	v_cvt_pk_bf16_f32 v36, v37, v36
	global_store_dword v[34:35], v36, off
	v_mul_f32_e32 v34, v42, v87
	v_mul_f32_e32 v35, v43, v88
	v_mul_f32_e32 v34, v34, v60
	v_mul_f32_e32 v35, v35, v60
	v_cndmask_b32_e32 v36, v34, v35, vcc
	ds_bpermute_b32 v36, v82, v36
	s_waitcnt lgkmcnt(0)
	v_cndmask_b32_e32 v37, v36, v34, vcc
	v_cndmask_b32_e32 v36, v35, v36, vcc
	v_lshl_add_u64 v[34:35], v[58:59], 0, v[56:57]
	v_mov_b32_e32 v38, v146
	v_lshlrev_b32_e32 v39, 16, v38
	v_mul_f32_e32 v40, 0xbfb8aa3b, v39
	v_exp_f32_e32 v40, v40
	v_and_b32_e32 v38, 0xffff0000, v38
	v_add_f32_e32 v40, 1.0, v40
	v_rcp_f32_e32 v40, v40
	s_nop 0
	v_mul_f32_e32 v39, v40, v39
	v_mul_f32_e32 v37, v37, v39
	v_mul_f32_e32 v39, 0xbfb8aa3b, v38
	v_exp_f32_e32 v39, v39
	s_nop 0
	v_add_f32_e32 v39, 1.0, v39
	v_rcp_f32_e32 v39, v39
	s_nop 0
	v_mul_f32_e32 v38, v39, v38
	v_mul_f32_e32 v36, v36, v38
	v_cvt_pk_bf16_f32 v36, v37, v36
	global_store_dword v[34:35], v36, off
	v_mul_f32_e32 v34, v44, v85
	v_mul_f32_e32 v35, v45, v86
	v_mul_f32_e32 v34, v34, v60
	v_mul_f32_e32 v35, v35, v60
	v_cndmask_b32_e32 v36, v34, v35, vcc
	ds_bpermute_b32 v36, v82, v36
	s_waitcnt lgkmcnt(0)
	v_cndmask_b32_e32 v37, v36, v34, vcc
	v_cndmask_b32_e32 v36, v35, v36, vcc
	v_lshl_add_u64 v[34:35], v[58:59], 0, v[54:55]
	v_mov_b32_e32 v38, v147
	v_lshlrev_b32_e32 v39, 16, v38
	v_mul_f32_e32 v40, 0xbfb8aa3b, v39
	v_exp_f32_e32 v40, v40
	v_and_b32_e32 v38, 0xffff0000, v38
	v_add_f32_e32 v40, 1.0, v40
	v_rcp_f32_e32 v40, v40
	s_nop 0
	v_mul_f32_e32 v39, v40, v39
	v_mul_f32_e32 v37, v37, v39
	v_mul_f32_e32 v39, 0xbfb8aa3b, v38
	v_exp_f32_e32 v39, v39
	s_nop 0
	v_add_f32_e32 v39, 1.0, v39
	v_rcp_f32_e32 v39, v39
	s_nop 0
	v_mul_f32_e32 v38, v39, v38
	v_mul_f32_e32 v36, v36, v38
	v_cvt_pk_bf16_f32 v36, v37, v36
	global_store_dword v[34:35], v36, off
	v_mul_f32_e32 v34, v46, v83
	v_mul_f32_e32 v35, v47, v84
	v_mul_f32_e32 v34, v34, v60
	v_mul_f32_e32 v35, v35, v60
	v_cndmask_b32_e32 v36, v34, v35, vcc
	ds_bpermute_b32 v36, v82, v36
	s_waitcnt lgkmcnt(0)
	v_cndmask_b32_e32 v37, v36, v34, vcc
	v_cndmask_b32_e32 v36, v35, v36, vcc
	v_lshl_add_u64 v[34:35], v[58:59], 0, v[52:53]
	v_mov_b32_e32 v38, v148
	v_lshlrev_b32_e32 v39, 16, v38
	v_mul_f32_e32 v40, 0xbfb8aa3b, v39
	v_exp_f32_e32 v40, v40
	v_and_b32_e32 v38, 0xffff0000, v38
	v_add_f32_e32 v40, 1.0, v40
	v_rcp_f32_e32 v40, v40
	s_nop 0
	v_mul_f32_e32 v39, v40, v39
	v_mul_f32_e32 v37, v37, v39
	v_mul_f32_e32 v39, 0xbfb8aa3b, v38
	v_exp_f32_e32 v39, v39
	s_nop 0
	v_add_f32_e32 v39, 1.0, v39
	v_rcp_f32_e32 v39, v39
	s_nop 0
	v_mul_f32_e32 v38, v39, v38
	v_mul_f32_e32 v36, v36, v38
	v_cvt_pk_bf16_f32 v36, v37, v36
	global_store_dword v[34:35], v36, off
	v_mul_f32_e32 v34, v48, v78
	v_mul_f32_e32 v35, v49, v79
	v_mul_f32_e32 v34, v34, v60
	v_mul_f32_e32 v35, v35, v60
	v_cndmask_b32_e32 v36, v34, v35, vcc
	ds_bpermute_b32 v36, v82, v36
	s_waitcnt lgkmcnt(0)
	v_cndmask_b32_e32 v37, v36, v34, vcc
	v_cndmask_b32_e32 v36, v35, v36, vcc
	v_lshl_add_u64 v[34:35], v[58:59], 0, v[50:51]
	v_mov_b32_e32 v38, v149
	v_lshlrev_b32_e32 v39, 16, v38
	v_mul_f32_e32 v40, 0xbfb8aa3b, v39
	v_exp_f32_e32 v40, v40
	v_and_b32_e32 v38, 0xffff0000, v38
	v_add_f32_e32 v40, 1.0, v40
	v_rcp_f32_e32 v40, v40
	s_nop 0
	v_mul_f32_e32 v39, v40, v39
	v_mul_f32_e32 v37, v37, v39
	v_mul_f32_e32 v39, 0xbfb8aa3b, v38
	v_exp_f32_e32 v39, v39
	s_nop 0
	v_add_f32_e32 v39, 1.0, v39
	v_rcp_f32_e32 v39, v39
	s_nop 0
	v_mul_f32_e32 v38, v39, v38
	v_mul_f32_e32 v36, v36, v38
	v_cvt_pk_bf16_f32 v36, v37, v36
	global_store_dword v[34:35], v36, off
	v_mov_b32_e32 v36, v168
	v_bitop3_b32 v34, v80, s0, 64 bitop3:0xc8
	v_lshlrev_b32_e32 v114, 1, v34
	v_lshl_add_u64 v[34:35], s[80:81], 0, v[114:115]
	s_movk_i32 s0, 0x3fe
	v_mul_f32_e32 v18, v18, v36
	v_mul_f32_e32 v19, v19, v36
	v_cndmask_b32_e32 v37, v18, v19, vcc
	ds_bpermute_b32 v37, v82, v37
	s_waitcnt lgkmcnt(0)
	v_cndmask_b32_e32 v38, v37, v18, vcc
	v_cndmask_b32_e32 v37, v19, v37, vcc
	v_lshl_add_u64 v[18:19], v[34:35], 0, v[72:73]
	v_mov_b32_e32 v39, v150
	v_lshlrev_b32_e32 v40, 16, v39
	v_mul_f32_e32 v41, 0xbfb8aa3b, v40
	v_exp_f32_e32 v41, v41
	v_and_b32_e32 v39, 0xffff0000, v39
	v_add_f32_e32 v41, 1.0, v41
	v_rcp_f32_e32 v41, v41
	s_nop 0
	v_mul_f32_e32 v40, v41, v40
	v_mul_f32_e32 v38, v38, v40
	v_mul_f32_e32 v40, 0xbfb8aa3b, v39
	v_exp_f32_e32 v40, v40
	s_nop 0
	v_add_f32_e32 v40, 1.0, v40
	v_rcp_f32_e32 v40, v40
	s_nop 0
	v_mul_f32_e32 v39, v40, v39
	v_mul_f32_e32 v37, v37, v39
	v_cvt_pk_bf16_f32 v37, v38, v37
	global_store_dword v[18:19], v37, off
	v_mul_f32_e32 v18, v20, v93
	v_mul_f32_e32 v19, v21, v95
	v_mul_f32_e32 v18, v18, v36
	v_mul_f32_e32 v19, v19, v36
	v_cndmask_b32_e32 v20, v18, v19, vcc
	ds_bpermute_b32 v20, v82, v20
	s_waitcnt lgkmcnt(0)
	v_cndmask_b32_e32 v21, v20, v18, vcc
	v_cndmask_b32_e32 v20, v19, v20, vcc
	v_lshl_add_u64 v[18:19], v[34:35], 0, v[70:71]
	v_mov_b32_e32 v37, v151
	v_lshlrev_b32_e32 v38, 16, v37
	v_mul_f32_e32 v39, 0xbfb8aa3b, v38
	v_exp_f32_e32 v39, v39
	v_and_b32_e32 v37, 0xffff0000, v37
	v_add_f32_e32 v39, 1.0, v39
	v_rcp_f32_e32 v39, v39
	s_nop 0
	v_mul_f32_e32 v38, v39, v38
	v_mul_f32_e32 v21, v21, v38
	v_mul_f32_e32 v38, 0xbfb8aa3b, v37
	v_exp_f32_e32 v38, v38
	s_nop 0
	v_add_f32_e32 v38, 1.0, v38
	v_rcp_f32_e32 v38, v38
	s_nop 0
	v_mul_f32_e32 v37, v38, v37
	v_mul_f32_e32 v20, v20, v37
	v_cvt_pk_bf16_f32 v20, v21, v20
	global_store_dword v[18:19], v20, off
	v_mul_f32_e32 v18, v22, v91
	v_mul_f32_e32 v19, v23, v92
	v_mul_f32_e32 v18, v18, v36
	v_mul_f32_e32 v19, v19, v36
	v_cndmask_b32_e32 v20, v18, v19, vcc
	ds_bpermute_b32 v20, v82, v20
	s_waitcnt lgkmcnt(0)
	v_cndmask_b32_e32 v21, v20, v18, vcc
	v_cndmask_b32_e32 v20, v19, v20, vcc
	v_lshl_add_u64 v[18:19], v[34:35], 0, v[68:69]
	v_mov_b32_e32 v22, v152
	v_lshlrev_b32_e32 v23, 16, v22
	v_mul_f32_e32 v37, 0xbfb8aa3b, v23
	v_exp_f32_e32 v37, v37
	v_and_b32_e32 v22, 0xffff0000, v22
	v_add_f32_e32 v37, 1.0, v37
	v_rcp_f32_e32 v37, v37
	s_nop 0
	v_mul_f32_e32 v23, v37, v23
	v_mul_f32_e32 v21, v21, v23
	v_mul_f32_e32 v23, 0xbfb8aa3b, v22
	v_exp_f32_e32 v23, v23
	s_nop 0
	v_add_f32_e32 v23, 1.0, v23
	v_rcp_f32_e32 v23, v23
	s_nop 0
	v_mul_f32_e32 v22, v23, v22
	v_mul_f32_e32 v20, v20, v22
	v_cvt_pk_bf16_f32 v20, v21, v20
	global_store_dword v[18:19], v20, off
	v_mul_f32_e32 v18, v24, v89
	v_mul_f32_e32 v19, v25, v90
	v_mul_f32_e32 v18, v18, v36
	v_mul_f32_e32 v19, v19, v36
	v_cndmask_b32_e32 v20, v18, v19, vcc
	ds_bpermute_b32 v20, v82, v20
	s_waitcnt lgkmcnt(0)
	v_cndmask_b32_e32 v21, v20, v18, vcc
	v_cndmask_b32_e32 v20, v19, v20, vcc
	v_lshl_add_u64 v[18:19], v[34:35], 0, v[66:67]
	v_mov_b32_e32 v22, v153
	v_lshlrev_b32_e32 v23, 16, v22
	v_mul_f32_e32 v24, 0xbfb8aa3b, v23
	v_exp_f32_e32 v24, v24
	v_and_b32_e32 v22, 0xffff0000, v22
	v_add_f32_e32 v24, 1.0, v24
	v_rcp_f32_e32 v24, v24
	s_nop 0
	v_mul_f32_e32 v23, v24, v23
	v_mul_f32_e32 v21, v21, v23
	v_mul_f32_e32 v23, 0xbfb8aa3b, v22
	v_exp_f32_e32 v23, v23
	s_nop 0
	v_add_f32_e32 v23, 1.0, v23
	v_rcp_f32_e32 v23, v23
	s_nop 0
	v_mul_f32_e32 v22, v23, v22
	v_mul_f32_e32 v20, v20, v22
	v_cvt_pk_bf16_f32 v20, v21, v20
	global_store_dword v[18:19], v20, off
	v_mul_f32_e32 v18, v26, v87
	v_mul_f32_e32 v19, v27, v88
	v_mul_f32_e32 v18, v18, v36
	v_mul_f32_e32 v19, v19, v36
	v_cndmask_b32_e32 v20, v18, v19, vcc
	ds_bpermute_b32 v20, v82, v20
	s_waitcnt lgkmcnt(0)
	v_cndmask_b32_e32 v21, v20, v18, vcc
	v_cndmask_b32_e32 v20, v19, v20, vcc
	v_lshl_add_u64 v[18:19], v[34:35], 0, v[56:57]
	v_mov_b32_e32 v22, v154
	v_lshlrev_b32_e32 v23, 16, v22
	v_mul_f32_e32 v24, 0xbfb8aa3b, v23
	v_exp_f32_e32 v24, v24
	v_and_b32_e32 v22, 0xffff0000, v22
	v_add_f32_e32 v24, 1.0, v24
	v_rcp_f32_e32 v24, v24
	s_nop 0
	v_mul_f32_e32 v23, v24, v23
	v_mul_f32_e32 v21, v21, v23
	v_mul_f32_e32 v23, 0xbfb8aa3b, v22
	v_exp_f32_e32 v23, v23
	s_nop 0
	v_add_f32_e32 v23, 1.0, v23
	v_rcp_f32_e32 v23, v23
	s_nop 0
	v_mul_f32_e32 v22, v23, v22
	v_mul_f32_e32 v20, v20, v22
	v_cvt_pk_bf16_f32 v20, v21, v20
	global_store_dword v[18:19], v20, off
	v_mul_f32_e32 v18, v28, v85
	v_mul_f32_e32 v19, v29, v86
	v_mul_f32_e32 v18, v18, v36
	v_mul_f32_e32 v19, v19, v36
	v_cndmask_b32_e32 v20, v18, v19, vcc
	ds_bpermute_b32 v20, v82, v20
	s_waitcnt lgkmcnt(0)
	v_cndmask_b32_e32 v21, v20, v18, vcc
	v_cndmask_b32_e32 v20, v19, v20, vcc
	v_lshl_add_u64 v[18:19], v[34:35], 0, v[54:55]
	v_mov_b32_e32 v22, v155
	v_lshlrev_b32_e32 v23, 16, v22
	v_mul_f32_e32 v24, 0xbfb8aa3b, v23
	v_exp_f32_e32 v24, v24
	v_and_b32_e32 v22, 0xffff0000, v22
	v_add_f32_e32 v24, 1.0, v24
	v_rcp_f32_e32 v24, v24
	s_nop 0
	v_mul_f32_e32 v23, v24, v23
	v_mul_f32_e32 v21, v21, v23
	v_mul_f32_e32 v23, 0xbfb8aa3b, v22
	v_exp_f32_e32 v23, v23
	s_nop 0
	v_add_f32_e32 v23, 1.0, v23
	v_rcp_f32_e32 v23, v23
	s_nop 0
	v_mul_f32_e32 v22, v23, v22
	v_mul_f32_e32 v20, v20, v22
	v_cvt_pk_bf16_f32 v20, v21, v20
	global_store_dword v[18:19], v20, off
	v_mul_f32_e32 v18, v30, v83
	v_mul_f32_e32 v19, v31, v84
	v_mul_f32_e32 v18, v18, v36
	v_mul_f32_e32 v19, v19, v36
	v_cndmask_b32_e32 v20, v18, v19, vcc
	ds_bpermute_b32 v20, v82, v20
	s_waitcnt lgkmcnt(0)
	v_cndmask_b32_e32 v21, v20, v18, vcc
	v_cndmask_b32_e32 v20, v19, v20, vcc
	v_lshl_add_u64 v[18:19], v[34:35], 0, v[52:53]
	v_mov_b32_e32 v22, v156
	v_lshlrev_b32_e32 v23, 16, v22
	v_mul_f32_e32 v24, 0xbfb8aa3b, v23
	v_exp_f32_e32 v24, v24
	v_and_b32_e32 v22, 0xffff0000, v22
	v_add_f32_e32 v24, 1.0, v24
	v_rcp_f32_e32 v24, v24
	s_nop 0
	v_mul_f32_e32 v23, v24, v23
	v_mul_f32_e32 v21, v21, v23
	v_mul_f32_e32 v23, 0xbfb8aa3b, v22
	v_exp_f32_e32 v23, v23
	s_nop 0
	v_add_f32_e32 v23, 1.0, v23
	v_rcp_f32_e32 v23, v23
	s_nop 0
	v_mul_f32_e32 v22, v23, v22
	v_mul_f32_e32 v20, v20, v22
	v_cvt_pk_bf16_f32 v20, v21, v20
	global_store_dword v[18:19], v20, off
	v_mul_f32_e32 v18, v32, v78
	v_mul_f32_e32 v19, v33, v79
	v_mul_f32_e32 v18, v18, v36
	v_mul_f32_e32 v19, v19, v36
	v_cndmask_b32_e32 v20, v18, v19, vcc
	ds_bpermute_b32 v20, v82, v20
	s_waitcnt lgkmcnt(0)
	v_cndmask_b32_e32 v21, v20, v18, vcc
	v_cndmask_b32_e32 v20, v19, v20, vcc
	v_lshl_add_u64 v[18:19], v[34:35], 0, v[50:51]
	v_mov_b32_e32 v22, v157
	v_lshlrev_b32_e32 v23, 16, v22
	v_mul_f32_e32 v24, 0xbfb8aa3b, v23
	v_exp_f32_e32 v24, v24
	v_and_b32_e32 v22, 0xffff0000, v22
	v_add_f32_e32 v24, 1.0, v24
	v_rcp_f32_e32 v24, v24
	s_nop 0
	v_mul_f32_e32 v23, v24, v23
	v_mul_f32_e32 v21, v21, v23
	v_mul_f32_e32 v23, 0xbfb8aa3b, v22
	v_exp_f32_e32 v23, v23
	s_nop 0
	v_add_f32_e32 v23, 1.0, v23
	v_rcp_f32_e32 v23, v23
	s_nop 0
	v_mul_f32_e32 v22, v23, v22
	v_mul_f32_e32 v20, v20, v22
	v_cvt_pk_bf16_f32 v20, v21, v20
	global_store_dword v[18:19], v20, off
	v_mov_b32_e32 v20, v169
	v_bitop3_b32 v18, v80, s0, v230 bitop3:0xc8
	v_lshlrev_b32_e32 v114, 1, v18
	v_lshl_add_u64 v[18:19], s[80:81], 0, v[114:115]
	v_mul_f32_e32 v2, v2, v20
	v_mul_f32_e32 v3, v3, v20
	v_cndmask_b32_e32 v21, v2, v3, vcc
	ds_bpermute_b32 v21, v82, v21
	s_waitcnt lgkmcnt(0)
	v_cndmask_b32_e32 v22, v21, v2, vcc
	v_cndmask_b32_e32 v21, v3, v21, vcc
	v_lshl_add_u64 v[2:3], v[18:19], 0, v[72:73]
	v_mov_b32_e32 v23, v158
	v_lshlrev_b32_e32 v24, 16, v23
	v_mul_f32_e32 v25, 0xbfb8aa3b, v24
	v_exp_f32_e32 v25, v25
	v_and_b32_e32 v23, 0xffff0000, v23
	v_add_f32_e32 v25, 1.0, v25
	v_rcp_f32_e32 v25, v25
	s_nop 0
	v_mul_f32_e32 v24, v25, v24
	v_mul_f32_e32 v22, v22, v24
	v_mul_f32_e32 v24, 0xbfb8aa3b, v23
	v_exp_f32_e32 v24, v24
	s_nop 0
	v_add_f32_e32 v24, 1.0, v24
	v_rcp_f32_e32 v24, v24
	s_nop 0
	v_mul_f32_e32 v23, v24, v23
	v_mul_f32_e32 v21, v21, v23
	v_cvt_pk_bf16_f32 v21, v22, v21
	global_store_dword v[2:3], v21, off
	v_mul_f32_e32 v2, v4, v93
	v_mul_f32_e32 v3, v5, v95
	v_mul_f32_e32 v2, v2, v20
	v_mul_f32_e32 v3, v3, v20
	v_cndmask_b32_e32 v4, v2, v3, vcc
	ds_bpermute_b32 v4, v82, v4
	s_waitcnt lgkmcnt(0)
	v_cndmask_b32_e32 v5, v4, v2, vcc
	v_cndmask_b32_e32 v4, v3, v4, vcc
	v_lshl_add_u64 v[2:3], v[18:19], 0, v[70:71]
	v_mov_b32_e32 v21, v159
	v_lshlrev_b32_e32 v22, 16, v21
	v_mul_f32_e32 v23, 0xbfb8aa3b, v22
	v_exp_f32_e32 v23, v23
	v_and_b32_e32 v21, 0xffff0000, v21
	v_add_f32_e32 v23, 1.0, v23
	v_rcp_f32_e32 v23, v23
	s_nop 0
	v_mul_f32_e32 v22, v23, v22
	v_mul_f32_e32 v5, v5, v22
	v_mul_f32_e32 v22, 0xbfb8aa3b, v21
	v_exp_f32_e32 v22, v22
	s_nop 0
	v_add_f32_e32 v22, 1.0, v22
	v_rcp_f32_e32 v22, v22
	s_nop 0
	v_mul_f32_e32 v21, v22, v21
	v_mul_f32_e32 v4, v4, v21
	v_cvt_pk_bf16_f32 v4, v5, v4
	global_store_dword v[2:3], v4, off
	v_mul_f32_e32 v2, v6, v91
	v_mul_f32_e32 v3, v7, v92
	v_mul_f32_e32 v2, v2, v20
	v_mul_f32_e32 v3, v3, v20
	v_cndmask_b32_e32 v4, v2, v3, vcc
	ds_bpermute_b32 v4, v82, v4
	s_waitcnt lgkmcnt(0)
	v_cndmask_b32_e32 v5, v4, v2, vcc
	v_cndmask_b32_e32 v4, v3, v4, vcc
	v_lshl_add_u64 v[2:3], v[18:19], 0, v[68:69]
	v_mov_b32_e32 v6, v160
	v_lshlrev_b32_e32 v7, 16, v6
	v_mul_f32_e32 v21, 0xbfb8aa3b, v7
	v_exp_f32_e32 v21, v21
	v_and_b32_e32 v6, 0xffff0000, v6
	v_add_f32_e32 v21, 1.0, v21
	v_rcp_f32_e32 v21, v21
	s_nop 0
	v_mul_f32_e32 v7, v21, v7
	v_mul_f32_e32 v5, v5, v7
	v_mul_f32_e32 v7, 0xbfb8aa3b, v6
	v_exp_f32_e32 v7, v7
	s_nop 0
	v_add_f32_e32 v7, 1.0, v7
	v_rcp_f32_e32 v7, v7
	s_nop 0
	v_mul_f32_e32 v6, v7, v6
	v_mul_f32_e32 v4, v4, v6
	v_cvt_pk_bf16_f32 v4, v5, v4
	global_store_dword v[2:3], v4, off
	v_mul_f32_e32 v2, v8, v89
	v_mul_f32_e32 v3, v9, v90
	v_mul_f32_e32 v2, v2, v20
	v_mul_f32_e32 v3, v3, v20
	v_cndmask_b32_e32 v4, v2, v3, vcc
	ds_bpermute_b32 v4, v82, v4
	s_waitcnt lgkmcnt(0)
	v_cndmask_b32_e32 v5, v4, v2, vcc
	v_cndmask_b32_e32 v4, v3, v4, vcc
	v_lshl_add_u64 v[2:3], v[18:19], 0, v[66:67]
	v_mov_b32_e32 v6, v161
	v_lshlrev_b32_e32 v7, 16, v6
	v_mul_f32_e32 v8, 0xbfb8aa3b, v7
	v_exp_f32_e32 v8, v8
	v_and_b32_e32 v6, 0xffff0000, v6
	v_add_f32_e32 v8, 1.0, v8
	v_rcp_f32_e32 v8, v8
	s_nop 0
	v_mul_f32_e32 v7, v8, v7
	v_mul_f32_e32 v5, v5, v7
	v_mul_f32_e32 v7, 0xbfb8aa3b, v6
	v_exp_f32_e32 v7, v7
	s_nop 0
	v_add_f32_e32 v7, 1.0, v7
	v_rcp_f32_e32 v7, v7
	s_nop 0
	v_mul_f32_e32 v6, v7, v6
	v_mul_f32_e32 v4, v4, v6
	v_cvt_pk_bf16_f32 v4, v5, v4
	global_store_dword v[2:3], v4, off
	v_mul_f32_e32 v2, v10, v87
	v_mul_f32_e32 v3, v11, v88
	v_mul_f32_e32 v2, v2, v20
	v_mul_f32_e32 v3, v3, v20
	v_cndmask_b32_e32 v4, v2, v3, vcc
	ds_bpermute_b32 v4, v82, v4
	s_waitcnt lgkmcnt(0)
	v_cndmask_b32_e32 v5, v4, v2, vcc
	v_cndmask_b32_e32 v4, v3, v4, vcc
	v_lshl_add_u64 v[2:3], v[18:19], 0, v[56:57]
	v_mov_b32_e32 v6, v162
	v_lshlrev_b32_e32 v7, 16, v6
	v_mul_f32_e32 v8, 0xbfb8aa3b, v7
	v_exp_f32_e32 v8, v8
	v_and_b32_e32 v6, 0xffff0000, v6
	v_add_f32_e32 v8, 1.0, v8
	v_rcp_f32_e32 v8, v8
	s_nop 0
	v_mul_f32_e32 v7, v8, v7
	v_mul_f32_e32 v5, v5, v7
	v_mul_f32_e32 v7, 0xbfb8aa3b, v6
	v_exp_f32_e32 v7, v7
	s_nop 0
	v_add_f32_e32 v7, 1.0, v7
	v_rcp_f32_e32 v7, v7
	s_nop 0
	v_mul_f32_e32 v6, v7, v6
	v_mul_f32_e32 v4, v4, v6
	v_cvt_pk_bf16_f32 v4, v5, v4
	global_store_dword v[2:3], v4, off
	v_mul_f32_e32 v2, v12, v85
	v_mul_f32_e32 v3, v13, v86
	v_mul_f32_e32 v2, v2, v20
	v_mul_f32_e32 v3, v3, v20
	v_cndmask_b32_e32 v4, v2, v3, vcc
	ds_bpermute_b32 v4, v82, v4
	s_waitcnt lgkmcnt(0)
	v_cndmask_b32_e32 v5, v4, v2, vcc
	v_cndmask_b32_e32 v4, v3, v4, vcc
	v_lshl_add_u64 v[2:3], v[18:19], 0, v[54:55]
	v_mov_b32_e32 v6, v163
	v_lshlrev_b32_e32 v7, 16, v6
	v_mul_f32_e32 v8, 0xbfb8aa3b, v7
	v_exp_f32_e32 v8, v8
	v_and_b32_e32 v6, 0xffff0000, v6
	v_add_f32_e32 v8, 1.0, v8
	v_rcp_f32_e32 v8, v8
	s_nop 0
	v_mul_f32_e32 v7, v8, v7
	v_mul_f32_e32 v5, v5, v7
	v_mul_f32_e32 v7, 0xbfb8aa3b, v6
	v_exp_f32_e32 v7, v7
	s_nop 0
	v_add_f32_e32 v7, 1.0, v7
	v_rcp_f32_e32 v7, v7
	s_nop 0
	v_mul_f32_e32 v6, v7, v6
	v_mul_f32_e32 v4, v4, v6
	v_cvt_pk_bf16_f32 v4, v5, v4
	global_store_dword v[2:3], v4, off
	v_mul_f32_e32 v2, v14, v83
	v_mul_f32_e32 v3, v15, v84
	v_mul_f32_e32 v2, v2, v20
	v_mul_f32_e32 v3, v3, v20
	v_cndmask_b32_e32 v4, v2, v3, vcc
	ds_bpermute_b32 v4, v82, v4
	s_waitcnt lgkmcnt(0)
	v_cndmask_b32_e32 v5, v4, v2, vcc
	v_cndmask_b32_e32 v4, v3, v4, vcc
	v_lshl_add_u64 v[2:3], v[18:19], 0, v[52:53]
	v_mov_b32_e32 v6, v164
	v_lshlrev_b32_e32 v7, 16, v6
	v_mul_f32_e32 v8, 0xbfb8aa3b, v7
	v_exp_f32_e32 v8, v8
	v_and_b32_e32 v6, 0xffff0000, v6
	v_add_f32_e32 v8, 1.0, v8
	v_rcp_f32_e32 v8, v8
	s_nop 0
	v_mul_f32_e32 v7, v8, v7
	v_mul_f32_e32 v5, v5, v7
	v_mul_f32_e32 v7, 0xbfb8aa3b, v6
	v_exp_f32_e32 v7, v7
	s_nop 0
	v_add_f32_e32 v7, 1.0, v7
	v_rcp_f32_e32 v7, v7
	s_nop 0
	v_mul_f32_e32 v6, v7, v6
	v_mul_f32_e32 v4, v4, v6
	v_cvt_pk_bf16_f32 v4, v5, v4
	global_store_dword v[2:3], v4, off
	v_mul_f32_e32 v2, v16, v78
	v_mul_f32_e32 v3, v17, v79
	v_mul_f32_e32 v2, v2, v20
	v_mul_f32_e32 v3, v3, v20
	v_cndmask_b32_e32 v4, v2, v3, vcc
	ds_bpermute_b32 v4, v82, v4
	s_waitcnt lgkmcnt(0)
	v_cndmask_b32_e32 v5, v4, v2, vcc
	v_cndmask_b32_e32 v4, v3, v4, vcc
	v_lshl_add_u64 v[2:3], v[18:19], 0, v[50:51]
	v_mov_b32_e32 v6, v165
	v_lshlrev_b32_e32 v7, 16, v6
	v_mul_f32_e32 v8, 0xbfb8aa3b, v7
	v_exp_f32_e32 v8, v8
	v_and_b32_e32 v6, 0xffff0000, v6
	v_add_f32_e32 v8, 1.0, v8
	v_rcp_f32_e32 v8, v8
	s_nop 0
	v_mul_f32_e32 v7, v8, v7
	v_mul_f32_e32 v5, v5, v7
	v_mul_f32_e32 v7, 0xbfb8aa3b, v6
	v_exp_f32_e32 v7, v7
	s_nop 0
	v_add_f32_e32 v7, 1.0, v7
	v_rcp_f32_e32 v7, v7
	s_nop 0
	v_mul_f32_e32 v6, v7, v6
	v_mul_f32_e32 v4, v4, v6
	v_cvt_pk_bf16_f32 v4, v5, v4
	global_store_dword v[2:3], v4, off
	s_nop 0
	s_nop 0
	s_nop 0
	s_nop 0

.LBB0_918:
	v_mov_b32_e32 v201, v115
	v_lshl_add_u64 v[34:35], v[200:201], 2, s[76:77]
	global_load_dword v34, v[34:35], off
	v_lshlrev_b32_e32 v88, 6, v200
	v_or_b32_e32 v114, v88, v231
	v_lshl_add_u64 v[38:39], v[114:115], 2, s[78:79]
	global_load_dword v35, v[38:39], off
	global_load_dword v49, v[38:39], off offset:128
	v_lshl_add_u64 v[40:41], v[114:115], 1, s[94:95]
	v_lshrrev_b32_e32 v36, 5, v88
	v_mov_b32_e32 v37, v115
	v_lshlrev_b64 v[36:37], 11, v[36:37]
	v_lshl_add_u64 v[42:43], v[36:37], 0, v[108:109]
	v_lshlrev_b64 v[42:43], 9, v[42:43]
	v_lshl_add_u64 v[42:43], v[104:105], 0, v[42:43]
	v_or_b32_e32 v36, 32, v88
	v_lshrrev_b32_e32 v36, 5, v36
	v_mov_b32_e32 v37, v115
	v_lshlrev_b64 v[36:37], 11, v[36:37]
	v_lshl_add_u64 v[44:45], v[36:37], 0, v[108:109]
	v_lshlrev_b64 v[44:45], 9, v[44:45]
	v_lshl_add_u64 v[44:45], v[104:105], 0, v[44:45]
	global_load_dwordx2 v[82:83], v[42:43], off
	global_load_dwordx2 v[84:85], v[42:43], off offset:512
	global_load_dwordx2 v[86:87], v[42:43], off offset:1024
	global_load_dwordx2 v[88:89], v[42:43], off offset:1536
	global_load_dwordx2 v[90:91], v[44:45], off
	global_load_dwordx2 v[92:93], v[44:45], off offset:512
	global_load_dwordx2 v[94:95], v[44:45], off offset:1024
	global_load_dwordx2 v[96:97], v[44:45], off offset:1536
	v_lshl_add_u64 v[202:203], v[40:41], 0, v[118:119]
	v_lshl_add_u64 v[204:205], v[40:41], 0, v[126:127]
	v_lshl_add_u64 v[206:207], v[40:41], 0, v[136:137]
	v_lshl_add_u64 v[208:209], v[40:41], 0, v[146:147]
	global_load_ushort v210, v[202:203], off offset:-4096
	global_load_ushort v211, v[202:203], off offset:-2048
	global_load_ushort v212, v[202:203], off
	global_load_ushort v213, v[202:203], off offset:2048
	global_load_ushort v214, v[204:205], off offset:-4096
	global_load_ushort v215, v[204:205], off offset:-2048
	global_load_ushort v216, v[204:205], off
	global_load_ushort v217, v[204:205], off offset:2048
	global_load_ushort v218, v[206:207], off offset:-4096
	global_load_ushort v219, v[206:207], off offset:-2048
	global_load_ushort v220, v[206:207], off
	global_load_ushort v221, v[206:207], off offset:2048
	global_load_ushort v222, v[208:209], off offset:-4096
	global_load_ushort v223, v[208:209], off offset:-2048
	global_load_ushort v224, v[208:209], off
	global_load_ushort v237, v[208:209], off offset:2048
	global_load_ushort v238, v[202:203], off offset:-4032
	global_load_ushort v239, v[202:203], off offset:-1984
	global_load_ushort v240, v[202:203], off offset:64
	global_load_ushort v241, v[202:203], off offset:2112
	global_load_ushort v242, v[204:205], off offset:-4032
	global_load_ushort v243, v[204:205], off offset:-1984
	global_load_ushort v244, v[204:205], off offset:64
	global_load_ushort v245, v[204:205], off offset:2112
	global_load_ushort v246, v[206:207], off offset:-4032
	global_load_ushort v247, v[206:207], off offset:-1984
	global_load_ushort v248, v[206:207], off offset:64
	global_load_ushort v249, v[206:207], off offset:2112
	global_load_ushort v46, v[208:209], off offset:-4032
	global_load_ushort v47, v[208:209], off offset:-1984
	global_load_ushort v48, v[208:209], off offset:64
	global_load_ushort v201, v[208:209], off offset:2112
	s_waitcnt vmcnt(0)
	v_lshlrev_b32_e32 v36, 16, v210
	v_lshlrev_b32_e32 v37, 16, v211
	v_mul_f32_e32 v38, 0xbfb8aa3b, v36
	v_mul_f32_e32 v39, 0xbfb8aa3b, v37
	v_exp_f32_e32 v38, v38
	v_exp_f32_e32 v39, v39
	v_lshlrev_b32_e32 v40, 16, v82
	v_and_b32_e32 v41, 0xffff0000, v82
	v_add_f32_e32 v38, 1.0, v38
	v_add_f32_e32 v39, 1.0, v39
	v_rcp_f32_e32 v38, v38
	v_rcp_f32_e32 v39, v39
	v_fma_f32 v18, v34, v40, v18
	v_fma_f32 v19, v34, v41, v19
	v_mul_f32_e32 v36, v38, v36
	v_mul_f32_e32 v37, v39, v37
	v_mul_f32_e32 v18, v18, v36
	v_mul_f32_e32 v19, v19, v37
	v_fma_f32 v198, v18, v18, v198
	v_fma_f32 v199, v19, v19, v199
	v_mul_f32_e32 v36, v35, v18
	v_mul_f32_e32 v37, v35, v19
	v_cvt_pk_bf16_f32 v36, v36, v36
	v_cvt_pk_bf16_f32 v37, v37, v37
	global_store_short v[202:203], v36, off offset:-4096
	global_store_short v[202:203], v37, off offset:-2048
	v_lshlrev_b32_e32 v36, 16, v238
	v_lshlrev_b32_e32 v37, 16, v239
	v_mul_f32_e32 v38, 0xbfb8aa3b, v36
	v_mul_f32_e32 v39, 0xbfb8aa3b, v37
	v_exp_f32_e32 v38, v38
	v_exp_f32_e32 v39, v39
	v_lshlrev_b32_e32 v40, 16, v90
	v_and_b32_e32 v41, 0xffff0000, v90
	v_add_f32_e32 v38, 1.0, v38
	v_add_f32_e32 v39, 1.0, v39
	v_rcp_f32_e32 v38, v38
	v_rcp_f32_e32 v39, v39
	v_fma_f32 v2, v34, v40, v2
	v_fma_f32 v3, v34, v41, v3
	v_mul_f32_e32 v36, v38, v36
	v_mul_f32_e32 v37, v39, v37
	v_mul_f32_e32 v2, v2, v36
	v_mul_f32_e32 v3, v3, v37
	v_fma_f32 v198, v2, v2, v198
	v_fma_f32 v199, v3, v3, v199
	v_mul_f32_e32 v36, v49, v2
	v_mul_f32_e32 v37, v49, v3
	v_cvt_pk_bf16_f32 v36, v36, v36
	v_cvt_pk_bf16_f32 v37, v37, v37
	global_store_short v[202:203], v36, off offset:-4032
	global_store_short v[202:203], v37, off offset:-1984
	v_lshlrev_b32_e32 v36, 16, v212
	v_lshlrev_b32_e32 v37, 16, v213
	v_mul_f32_e32 v38, 0xbfb8aa3b, v36
	v_mul_f32_e32 v39, 0xbfb8aa3b, v37
	v_exp_f32_e32 v38, v38
	v_exp_f32_e32 v39, v39
	v_lshlrev_b32_e32 v40, 16, v83
	v_and_b32_e32 v41, 0xffff0000, v83
	v_add_f32_e32 v38, 1.0, v38
	v_add_f32_e32 v39, 1.0, v39
	v_rcp_f32_e32 v38, v38
	v_rcp_f32_e32 v39, v39
	v_fma_f32 v20, v34, v40, v20
	v_fma_f32 v21, v34, v41, v21
	v_mul_f32_e32 v36, v38, v36
	v_mul_f32_e32 v37, v39, v37
	v_mul_f32_e32 v20, v20, v36
	v_mul_f32_e32 v21, v21, v37
	v_fma_f32 v194, v20, v20, v194
	v_fma_f32 v195, v21, v21, v195
	v_mul_f32_e32 v36, v35, v20
	v_mul_f32_e32 v37, v35, v21
	v_cvt_pk_bf16_f32 v36, v36, v36
	v_cvt_pk_bf16_f32 v37, v37, v37
	global_store_short v[202:203], v36, off
	global_store_short v[202:203], v37, off offset:2048
	v_lshlrev_b32_e32 v36, 16, v240
	v_lshlrev_b32_e32 v37, 16, v241
	v_mul_f32_e32 v38, 0xbfb8aa3b, v36
	v_mul_f32_e32 v39, 0xbfb8aa3b, v37
	v_exp_f32_e32 v38, v38
	v_exp_f32_e32 v39, v39
	v_lshlrev_b32_e32 v40, 16, v91
	v_and_b32_e32 v41, 0xffff0000, v91
	v_add_f32_e32 v38, 1.0, v38
	v_add_f32_e32 v39, 1.0, v39
	v_rcp_f32_e32 v38, v38
	v_rcp_f32_e32 v39, v39
	v_fma_f32 v4, v34, v40, v4
	v_fma_f32 v5, v34, v41, v5
	v_mul_f32_e32 v36, v38, v36
	v_mul_f32_e32 v37, v39, v37
	v_mul_f32_e32 v4, v4, v36
	v_mul_f32_e32 v5, v5, v37
	v_fma_f32 v194, v4, v4, v194
	v_fma_f32 v195, v5, v5, v195
	v_mul_f32_e32 v36, v49, v4
	v_mul_f32_e32 v37, v49, v5
	v_cvt_pk_bf16_f32 v36, v36, v36
	v_cvt_pk_bf16_f32 v37, v37, v37
	global_store_short v[202:203], v36, off offset:64
	global_store_short v[202:203], v37, off offset:2112
	v_lshlrev_b32_e32 v36, 16, v214
	v_lshlrev_b32_e32 v37, 16, v215
	v_mul_f32_e32 v38, 0xbfb8aa3b, v36
	v_mul_f32_e32 v39, 0xbfb8aa3b, v37
	v_exp_f32_e32 v38, v38
	v_exp_f32_e32 v39, v39
	v_lshlrev_b32_e32 v40, 16, v84
	v_and_b32_e32 v41, 0xffff0000, v84
	v_add_f32_e32 v38, 1.0, v38
	v_add_f32_e32 v39, 1.0, v39
	v_rcp_f32_e32 v38, v38
	v_rcp_f32_e32 v39, v39
	v_fma_f32 v22, v34, v40, v22
	v_fma_f32 v23, v34, v41, v23
	v_mul_f32_e32 v36, v38, v36
	v_mul_f32_e32 v37, v39, v37
	v_mul_f32_e32 v22, v22, v36
	v_mul_f32_e32 v23, v23, v37
	v_fma_f32 v196, v22, v22, v196
	v_fma_f32 v197, v23, v23, v197
	v_mul_f32_e32 v36, v35, v22
	v_mul_f32_e32 v37, v35, v23
	v_cvt_pk_bf16_f32 v36, v36, v36
	v_cvt_pk_bf16_f32 v37, v37, v37
	global_store_short v[204:205], v36, off offset:-4096
	global_store_short v[204:205], v37, off offset:-2048
	v_lshlrev_b32_e32 v36, 16, v242
	v_lshlrev_b32_e32 v37, 16, v243
	v_mul_f32_e32 v38, 0xbfb8aa3b, v36
	v_mul_f32_e32 v39, 0xbfb8aa3b, v37
	v_exp_f32_e32 v38, v38
	v_exp_f32_e32 v39, v39
	v_lshlrev_b32_e32 v40, 16, v92
	v_and_b32_e32 v41, 0xffff0000, v92
	v_add_f32_e32 v38, 1.0, v38
	v_add_f32_e32 v39, 1.0, v39
	v_rcp_f32_e32 v38, v38
	v_rcp_f32_e32 v39, v39
	v_fma_f32 v6, v34, v40, v6
	v_fma_f32 v7, v34, v41, v7
	v_mul_f32_e32 v36, v38, v36
	v_mul_f32_e32 v37, v39, v37
	v_mul_f32_e32 v6, v6, v36
	v_mul_f32_e32 v7, v7, v37
	v_fma_f32 v196, v6, v6, v196
	v_fma_f32 v197, v7, v7, v197
	v_mul_f32_e32 v36, v49, v6
	v_mul_f32_e32 v37, v49, v7
	v_cvt_pk_bf16_f32 v36, v36, v36
	v_cvt_pk_bf16_f32 v37, v37, v37
	global_store_short v[204:205], v36, off offset:-4032
	global_store_short v[204:205], v37, off offset:-1984
	v_lshlrev_b32_e32 v36, 16, v216
	v_lshlrev_b32_e32 v37, 16, v217
	v_mul_f32_e32 v38, 0xbfb8aa3b, v36
	v_mul_f32_e32 v39, 0xbfb8aa3b, v37
	v_exp_f32_e32 v38, v38
	v_exp_f32_e32 v39, v39
	v_lshlrev_b32_e32 v40, 16, v85
	v_and_b32_e32 v41, 0xffff0000, v85
	v_add_f32_e32 v38, 1.0, v38
	v_add_f32_e32 v39, 1.0, v39
	v_rcp_f32_e32 v38, v38
	v_rcp_f32_e32 v39, v39
	v_fma_f32 v24, v34, v40, v24
	v_fma_f32 v25, v34, v41, v25
	v_mul_f32_e32 v36, v38, v36
	v_mul_f32_e32 v37, v39, v37
	v_mul_f32_e32 v24, v24, v36
	v_mul_f32_e32 v25, v25, v37
	v_fma_f32 v186, v24, v24, v186
	v_fma_f32 v187, v25, v25, v187
	v_mul_f32_e32 v36, v35, v24
	v_mul_f32_e32 v37, v35, v25
	v_cvt_pk_bf16_f32 v36, v36, v36
	v_cvt_pk_bf16_f32 v37, v37, v37
	global_store_short v[204:205], v36, off
	global_store_short v[204:205], v37, off offset:2048
	v_lshlrev_b32_e32 v36, 16, v244
	v_lshlrev_b32_e32 v37, 16, v245
	v_mul_f32_e32 v38, 0xbfb8aa3b, v36
	v_mul_f32_e32 v39, 0xbfb8aa3b, v37
	v_exp_f32_e32 v38, v38
	v_exp_f32_e32 v39, v39
	v_lshlrev_b32_e32 v40, 16, v93
	v_and_b32_e32 v41, 0xffff0000, v93
	v_add_f32_e32 v38, 1.0, v38
	v_add_f32_e32 v39, 1.0, v39
	v_rcp_f32_e32 v38, v38
	v_rcp_f32_e32 v39, v39
	v_fma_f32 v8, v34, v40, v8
	v_fma_f32 v9, v34, v41, v9
	v_mul_f32_e32 v36, v38, v36
	v_mul_f32_e32 v37, v39, v37
	v_mul_f32_e32 v8, v8, v36
	v_mul_f32_e32 v9, v9, v37
	v_fma_f32 v186, v8, v8, v186
	v_fma_f32 v187, v9, v9, v187
	v_mul_f32_e32 v36, v49, v8
	v_mul_f32_e32 v37, v49, v9
	v_cvt_pk_bf16_f32 v36, v36, v36
	v_cvt_pk_bf16_f32 v37, v37, v37
	global_store_short v[204:205], v36, off offset:64
	global_store_short v[204:205], v37, off offset:2112
	v_lshlrev_b32_e32 v36, 16, v218
	v_lshlrev_b32_e32 v37, 16, v219
	v_mul_f32_e32 v38, 0xbfb8aa3b, v36
	v_mul_f32_e32 v39, 0xbfb8aa3b, v37
	v_exp_f32_e32 v38, v38
	v_exp_f32_e32 v39, v39
	v_lshlrev_b32_e32 v40, 16, v86
	v_and_b32_e32 v41, 0xffff0000, v86
	v_add_f32_e32 v38, 1.0, v38
	v_add_f32_e32 v39, 1.0, v39
	v_rcp_f32_e32 v38, v38
	v_rcp_f32_e32 v39, v39
	v_fma_f32 v26, v34, v40, v26
	v_fma_f32 v27, v34, v41, v27
	v_mul_f32_e32 v36, v38, v36
	v_mul_f32_e32 v37, v39, v37
	v_mul_f32_e32 v26, v26, v36
	v_mul_f32_e32 v27, v27, v37
	v_fma_f32 v190, v26, v26, v190
	v_fma_f32 v191, v27, v27, v191
	v_mul_f32_e32 v36, v35, v26
	v_mul_f32_e32 v37, v35, v27
	v_cvt_pk_bf16_f32 v36, v36, v36
	v_cvt_pk_bf16_f32 v37, v37, v37
	global_store_short v[206:207], v36, off offset:-4096
	global_store_short v[206:207], v37, off offset:-2048
	v_lshlrev_b32_e32 v36, 16, v246
	v_lshlrev_b32_e32 v37, 16, v247
	v_mul_f32_e32 v38, 0xbfb8aa3b, v36
	v_mul_f32_e32 v39, 0xbfb8aa3b, v37
	v_exp_f32_e32 v38, v38
	v_exp_f32_e32 v39, v39
	v_lshlrev_b32_e32 v40, 16, v94
	v_and_b32_e32 v41, 0xffff0000, v94
	v_add_f32_e32 v38, 1.0, v38
	v_add_f32_e32 v39, 1.0, v39
	v_rcp_f32_e32 v38, v38
	v_rcp_f32_e32 v39, v39
	v_fma_f32 v10, v34, v40, v10
	v_fma_f32 v11, v34, v41, v11
	v_mul_f32_e32 v36, v38, v36
	v_mul_f32_e32 v37, v39, v37
	v_mul_f32_e32 v10, v10, v36
	v_mul_f32_e32 v11, v11, v37
	v_fma_f32 v190, v10, v10, v190
	v_fma_f32 v191, v11, v11, v191
	v_mul_f32_e32 v36, v49, v10
	v_mul_f32_e32 v37, v49, v11
	v_cvt_pk_bf16_f32 v36, v36, v36
	v_cvt_pk_bf16_f32 v37, v37, v37
	global_store_short v[206:207], v36, off offset:-4032
	global_store_short v[206:207], v37, off offset:-1984
	v_lshlrev_b32_e32 v36, 16, v220
	v_lshlrev_b32_e32 v37, 16, v221
	v_mul_f32_e32 v38, 0xbfb8aa3b, v36
	v_mul_f32_e32 v39, 0xbfb8aa3b, v37
	v_exp_f32_e32 v38, v38
	v_exp_f32_e32 v39, v39
	v_lshlrev_b32_e32 v40, 16, v87
	v_and_b32_e32 v41, 0xffff0000, v87
	v_add_f32_e32 v38, 1.0, v38
	v_add_f32_e32 v39, 1.0, v39
	v_rcp_f32_e32 v38, v38
	v_rcp_f32_e32 v39, v39
	v_fma_f32 v28, v34, v40, v28
	v_fma_f32 v29, v34, v41, v29
	v_mul_f32_e32 v36, v38, v36
	v_mul_f32_e32 v37, v39, v37
	v_mul_f32_e32 v28, v28, v36
	v_mul_f32_e32 v29, v29, v37
	v_fma_f32 v192, v28, v28, v192
	v_fma_f32 v193, v29, v29, v193
	v_mul_f32_e32 v36, v35, v28
	v_mul_f32_e32 v37, v35, v29
	v_cvt_pk_bf16_f32 v36, v36, v36
	v_cvt_pk_bf16_f32 v37, v37, v37
	global_store_short v[206:207], v36, off
	global_store_short v[206:207], v37, off offset:2048
	v_lshlrev_b32_e32 v36, 16, v248
	v_lshlrev_b32_e32 v37, 16, v249
	v_mul_f32_e32 v38, 0xbfb8aa3b, v36
	v_mul_f32_e32 v39, 0xbfb8aa3b, v37
	v_exp_f32_e32 v38, v38
	v_exp_f32_e32 v39, v39
	v_lshlrev_b32_e32 v40, 16, v95
	v_and_b32_e32 v41, 0xffff0000, v95
	v_add_f32_e32 v38, 1.0, v38
	v_add_f32_e32 v39, 1.0, v39
	v_rcp_f32_e32 v38, v38
	v_rcp_f32_e32 v39, v39
	v_fma_f32 v12, v34, v40, v12
	v_fma_f32 v13, v34, v41, v13
	v_mul_f32_e32 v36, v38, v36
	v_mul_f32_e32 v37, v39, v37
	v_mul_f32_e32 v12, v12, v36
	v_mul_f32_e32 v13, v13, v37
	v_fma_f32 v192, v12, v12, v192
	v_fma_f32 v193, v13, v13, v193
	v_mul_f32_e32 v36, v49, v12
	v_mul_f32_e32 v37, v49, v13
	v_cvt_pk_bf16_f32 v36, v36, v36
	v_cvt_pk_bf16_f32 v37, v37, v37
	global_store_short v[206:207], v36, off offset:64
	global_store_short v[206:207], v37, off offset:2112
	v_lshlrev_b32_e32 v36, 16, v222
	v_lshlrev_b32_e32 v37, 16, v223
	v_mul_f32_e32 v38, 0xbfb8aa3b, v36
	v_mul_f32_e32 v39, 0xbfb8aa3b, v37
	v_exp_f32_e32 v38, v38
	v_exp_f32_e32 v39, v39
	v_lshlrev_b32_e32 v40, 16, v88
	v_and_b32_e32 v41, 0xffff0000, v88
	v_add_f32_e32 v38, 1.0, v38
	v_add_f32_e32 v39, 1.0, v39
	v_rcp_f32_e32 v38, v38
	v_rcp_f32_e32 v39, v39
	v_fma_f32 v30, v34, v40, v30
	v_fma_f32 v31, v34, v41, v31
	v_mul_f32_e32 v36, v38, v36
	v_mul_f32_e32 v37, v39, v37
	v_mul_f32_e32 v30, v30, v36
	v_mul_f32_e32 v31, v31, v37
	v_fma_f32 v188, v30, v30, v188
	v_fma_f32 v189, v31, v31, v189
	v_mul_f32_e32 v36, v35, v30
	v_mul_f32_e32 v37, v35, v31
	v_cvt_pk_bf16_f32 v36, v36, v36
	v_cvt_pk_bf16_f32 v37, v37, v37
	global_store_short v[208:209], v36, off offset:-4096
	global_store_short v[208:209], v37, off offset:-2048
	v_lshlrev_b32_e32 v36, 16, v46
	v_lshlrev_b32_e32 v37, 16, v47
	v_mul_f32_e32 v38, 0xbfb8aa3b, v36
	v_mul_f32_e32 v39, 0xbfb8aa3b, v37
	v_exp_f32_e32 v38, v38
	v_exp_f32_e32 v39, v39
	v_lshlrev_b32_e32 v40, 16, v96
	v_and_b32_e32 v41, 0xffff0000, v96
	v_add_f32_e32 v38, 1.0, v38
	v_add_f32_e32 v39, 1.0, v39
	v_rcp_f32_e32 v38, v38
	v_rcp_f32_e32 v39, v39
	v_fma_f32 v14, v34, v40, v14
	v_fma_f32 v15, v34, v41, v15
	v_mul_f32_e32 v36, v38, v36
	v_mul_f32_e32 v37, v39, v37
	v_mul_f32_e32 v14, v14, v36
	v_mul_f32_e32 v15, v15, v37
	v_fma_f32 v188, v14, v14, v188
	v_fma_f32 v189, v15, v15, v189
	v_mul_f32_e32 v36, v49, v14
	v_mul_f32_e32 v37, v49, v15
	v_cvt_pk_bf16_f32 v36, v36, v36
	v_cvt_pk_bf16_f32 v37, v37, v37
	global_store_short v[208:209], v36, off offset:-4032
	global_store_short v[208:209], v37, off offset:-1984
	v_lshlrev_b32_e32 v36, 16, v224
	v_lshlrev_b32_e32 v37, 16, v237
	v_mul_f32_e32 v38, 0xbfb8aa3b, v36
	v_mul_f32_e32 v39, 0xbfb8aa3b, v37
	v_exp_f32_e32 v38, v38
	v_exp_f32_e32 v39, v39
	v_lshlrev_b32_e32 v40, 16, v89
	v_and_b32_e32 v41, 0xffff0000, v89
	v_add_f32_e32 v38, 1.0, v38
	v_add_f32_e32 v39, 1.0, v39
	v_rcp_f32_e32 v38, v38
	v_rcp_f32_e32 v39, v39
	v_fma_f32 v32, v34, v40, v32
	v_fma_f32 v33, v34, v41, v33
	v_mul_f32_e32 v36, v38, v36
	v_mul_f32_e32 v37, v39, v37
	v_mul_f32_e32 v32, v32, v36
	v_mul_f32_e32 v33, v33, v37
	v_fma_f32 v184, v32, v32, v184
	v_fma_f32 v185, v33, v33, v185
	v_mul_f32_e32 v36, v35, v32
	v_mul_f32_e32 v37, v35, v33
	v_cvt_pk_bf16_f32 v36, v36, v36
	v_cvt_pk_bf16_f32 v37, v37, v37
	global_store_short v[208:209], v36, off
	global_store_short v[208:209], v37, off offset:2048
	v_lshlrev_b32_e32 v36, 16, v48
	v_lshlrev_b32_e32 v37, 16, v201
	v_mul_f32_e32 v38, 0xbfb8aa3b, v36
	v_mul_f32_e32 v39, 0xbfb8aa3b, v37
	v_exp_f32_e32 v38, v38
	v_exp_f32_e32 v39, v39
	v_lshlrev_b32_e32 v40, 16, v97
	v_and_b32_e32 v41, 0xffff0000, v97
	v_add_f32_e32 v38, 1.0, v38
	v_add_f32_e32 v39, 1.0, v39
	v_rcp_f32_e32 v38, v38
	v_rcp_f32_e32 v39, v39
	v_fma_f32 v16, v34, v40, v16
	v_fma_f32 v17, v34, v41, v17
	v_mul_f32_e32 v36, v38, v36
	v_mul_f32_e32 v37, v39, v37
	v_mul_f32_e32 v16, v16, v36
	v_mul_f32_e32 v17, v17, v37
	v_fma_f32 v184, v16, v16, v184
	v_fma_f32 v185, v17, v17, v185
	v_mul_f32_e32 v36, v49, v16
	v_mul_f32_e32 v37, v49, v17
	v_cvt_pk_bf16_f32 v36, v36, v36
	v_cvt_pk_bf16_f32 v37, v37, v37
	global_store_short v[208:209], v36, off offset:64
	global_store_short v[208:209], v37, off offset:2112
	v_cmp_eq_u32_e32 vcc, v236, v234
	v_add_u32_e32 v235, 4, v235
	s_or_b64 s[2:3], vcc, s[2:3]
	v_add_u32_e32 v236, 1, v236
	s_andn2_b64 exec, exec, s[2:3]
	s_cbranch_execz .LBB0_922
.LBB0_919:
	v_add_u32_e32 v200, v236, v99
	v_add_u32_e32 v2, v200, v101
	v_ashrrev_i32_e32 v3, 31, v2
	v_lshlrev_b64 v[2:3], 14, v[2:3]
	v_lshl_add_u64 v[22:23], v[150:151], 0, v[2:3]
	v_add_co_u32_e32 v202, vcc, s97, v22
	s_nop 1
	v_addc_co_u32_e32 v203, vcc, 0, v23, vcc
	v_add_co_u32_e32 v204, vcc, s82, v22
	s_nop 1
	v_addc_co_u32_e32 v205, vcc, 0, v23, vcc
	global_load_dwordx4 v[18:21], v[202:203], off offset:-4096
	global_load_dwordx4 v[22:25], v[204:205], off offset:-4096
	global_load_dwordx4 v[26:29], v[202:203], off offset:-3072
	global_load_dwordx4 v[30:33], v[204:205], off offset:-3072
	global_load_dwordx4 v[82:85], v[202:203], off offset:-2048
	global_load_dwordx4 v[86:89], v[204:205], off offset:-2048
	global_load_dwordx4 v[90:93], v[202:203], off offset:-1024
	global_load_dwordx4 v[94:97], v[204:205], off offset:-1024
	s_waitcnt vmcnt(7)
	v_mfma_f32_32x32x16_bf16 v[2:17], v[50:53], v[18:21], 0
	global_load_dwordx4 v[18:21], v[202:203], off
	s_waitcnt vmcnt(7)
	v_mfma_f32_32x32x16_bf16 v[34:49], v[50:53], v[22:25], 0
	global_load_dwordx4 v[22:25], v[204:205], off
	s_waitcnt vmcnt(7)
	v_mfma_f32_32x32x16_bf16 v[2:17], v[54:57], v[26:29], v[2:17]
	global_load_dwordx4 v[26:29], v[202:203], off offset:1024
	s_waitcnt vmcnt(7)
	v_mfma_f32_32x32x16_bf16 v[34:49], v[54:57], v[30:33], v[34:49]
	global_load_dwordx4 v[30:33], v[204:205], off offset:1024
	s_waitcnt vmcnt(7)
	v_mfma_f32_32x32x16_bf16 v[2:17], v[58:61], v[82:85], v[2:17]
	global_load_dwordx4 v[82:85], v[202:203], off offset:2048
	s_waitcnt vmcnt(7)
	v_mfma_f32_32x32x16_bf16 v[34:49], v[58:61], v[86:89], v[34:49]
	global_load_dwordx4 v[86:89], v[204:205], off offset:2048
	s_waitcnt vmcnt(7)
	v_mfma_f32_32x32x16_bf16 v[2:17], v[62:65], v[90:93], v[2:17]
	global_load_dwordx4 v[90:93], v[202:203], off offset:3072
	s_waitcnt vmcnt(7)
	v_mfma_f32_32x32x16_bf16 v[34:49], v[62:65], v[94:97], v[34:49]
	global_load_dwordx4 v[94:97], v[204:205], off offset:3072
	s_waitcnt vmcnt(7)
	v_mfma_f32_32x32x16_bf16 v[2:17], v[66:69], v[18:21], v[2:17]
	s_waitcnt vmcnt(6)
	v_mfma_f32_32x32x16_bf16 v[34:49], v[66:69], v[22:25], v[34:49]
	s_waitcnt vmcnt(5)
	v_mfma_f32_32x32x16_bf16 v[2:17], v[70:73], v[26:29], v[2:17]
	s_waitcnt vmcnt(4)
	v_mfma_f32_32x32x16_bf16 v[34:49], v[70:73], v[30:33], v[34:49]
	s_waitcnt vmcnt(3)
	v_mfma_f32_32x32x16_bf16 v[2:17], v[74:77], v[82:85], v[2:17]
	s_waitcnt vmcnt(2)
	v_mfma_f32_32x32x16_bf16 v[34:49], v[74:77], v[86:89], v[34:49]
	s_waitcnt vmcnt(1)
	v_mfma_f32_32x32x16_bf16 v[2:17], v[78:81], v[90:93], v[2:17]
	s_waitcnt vmcnt(0)
	v_mfma_f32_32x32x16_bf16 v[34:49], v[78:81], v[94:97], v[34:49]
	s_andn2_b64 vcc, exec, s[38:39]
	s_nop 0
	s_nop 0
	s_nop 0
	s_nop 0
	s_nop 0
	v_lshlrev_b32_e32 v18, 2, v236
	v_add3_u32 v20, v225, v18, v233
	ds_read2_b32 v[18:19], v20 offset1:8
	s_waitcnt lgkmcnt(0)
	v_mul_f32_e32 v18, 0x3fb8aa3b, v18
	v_exp_f32_e32 v82, v18
	v_mul_f32_e32 v18, 0x3fb8aa3b, v19
	v_exp_f32_e32 v83, v18
	ds_read2_b32 v[18:19], v20 offset0:16 offset1:24
	s_waitcnt lgkmcnt(0)
	v_mul_f32_e32 v18, 0x3fb8aa3b, v18
	v_exp_f32_e32 v84, v18
	v_mul_f32_e32 v18, 0x3fb8aa3b, v19
	v_exp_f32_e32 v85, v18
	ds_read2_b32 v[18:19], v20 offset0:64 offset1:72
	s_waitcnt lgkmcnt(0)
	v_mul_f32_e32 v18, 0x3fb8aa3b, v18
	v_exp_f32_e32 v86, v18
	v_mul_f32_e32 v18, 0x3fb8aa3b, v19
	v_exp_f32_e32 v87, v18
	ds_read2_b32 v[18:19], v20 offset0:80 offset1:88
	v_pk_mul_f32 v[22:23], v[6:7], v[86:87]
	v_pk_mul_f32 v[6:7], v[38:39], v[86:87]
	s_waitcnt lgkmcnt(0)
	v_mul_f32_e32 v18, 0x3fb8aa3b, v18
	v_exp_f32_e32 v88, v18
	v_mul_f32_e32 v18, 0x3fb8aa3b, v19
	v_exp_f32_e32 v89, v18
	ds_read2_b32 v[18:19], v20 offset0:128 offset1:136
	v_pk_mul_f32 v[24:25], v[8:9], v[88:89]
	v_pk_mul_f32 v[8:9], v[40:41], v[88:89]
	s_waitcnt lgkmcnt(0)
	v_mul_f32_e32 v18, 0x3fb8aa3b, v18
	v_exp_f32_e32 v90, v18
	v_mul_f32_e32 v18, 0x3fb8aa3b, v19
	v_exp_f32_e32 v91, v18
	ds_read2_b32 v[18:19], v20 offset0:144 offset1:152
	v_pk_mul_f32 v[26:27], v[10:11], v[90:91]
	v_pk_mul_f32 v[10:11], v[42:43], v[90:91]
	s_waitcnt lgkmcnt(0)
	v_mul_f32_e32 v18, 0x3fb8aa3b, v18
	v_exp_f32_e32 v92, v18
	v_mul_f32_e32 v18, 0x3fb8aa3b, v19
	v_exp_f32_e32 v93, v18
	ds_read2_b32 v[18:19], v20 offset0:192 offset1:200
	v_pk_mul_f32 v[28:29], v[12:13], v[92:93]
	v_pk_mul_f32 v[12:13], v[44:45], v[92:93]
	s_waitcnt lgkmcnt(0)
	v_mul_f32_e32 v18, 0x3fb8aa3b, v18
	v_exp_f32_e32 v94, v18
	v_mul_f32_e32 v18, 0x3fb8aa3b, v19
	v_exp_f32_e32 v95, v18
	ds_read2_b32 v[18:19], v20 offset0:208 offset1:216
	v_pk_mul_f32 v[20:21], v[4:5], v[84:85]
	v_pk_mul_f32 v[4:5], v[36:37], v[84:85]
	v_pk_mul_f32 v[30:31], v[14:15], v[94:95]
	v_pk_mul_f32 v[14:15], v[46:47], v[94:95]
	s_waitcnt lgkmcnt(0)
	v_mul_f32_e32 v18, 0x3fb8aa3b, v18
	v_exp_f32_e32 v96, v18
	v_mul_f32_e32 v18, 0x3fb8aa3b, v19
	v_exp_f32_e32 v97, v18
	v_pk_mul_f32 v[18:19], v[2:3], v[82:83]
	v_pk_mul_f32 v[2:3], v[34:35], v[82:83]
	v_pk_mul_f32 v[32:33], v[16:17], v[96:97]
	v_pk_mul_f32 v[16:17], v[48:49], v[96:97]
	s_cbranch_vccnz .LBB0_918
	v_lshl_add_u32 v34, v236, 2, v117
	ds_read_b32 v201, v34
	v_lshlrev_b32_e32 v114, 1, v200
	v_lshlrev_b64 v[202:203], 20, v[114:115]
	v_or_b32_e32 v114, 1, v114
	v_lshlrev_b64 v[204:205], 20, v[114:115]
	s_mov_b32 s86, 0
	v_mov_b32_e32 v206, v98
	v_mov_b32_e32 v207, v235

.LBB0_954:
	s_or_b64 exec, exec, s[72:73]
	s_movk_i32 s0, 0x1ff
	v_cmp_lt_i32_e32 vcc, s0, v1
	s_and_saveexec_b64 s[36:37], vcc
	s_cbranch_execz .LBB0_900
	v_add_u32_e32 v2, 0xfffffe00, v1
	v_lshrrev_b32_e32 v3, 9, v2
	v_xor_b32_e32 v3, v3, v1
	v_lshlrev_b32_e32 v3, 1, v3
	v_lshrrev_b32_e32 v4, 3, v2
	v_and_b32_e32 v3, 2, v3
	s_ashr_i32 s0, s85, 7
	v_lshlrev_b32_e32 v2, 7, v4
	v_add_u32_e32 v74, s0, v3
	v_lshl_add_u32 v117, v74, 5, v2
	v_or_b32_e32 v2, v117, v231
	v_ashrrev_i32_e32 v3, 31, v2
	v_readlane_b32 s0, v253, 63
	v_bfe_u32 v75, v1, 1, 2
	v_lshlrev_b64 v[2:3], 10, v[2:3]
	v_readlane_b32 s1, v254, 0
	v_lshlrev_b32_e32 v118, 8, v75
	v_mov_b32_e32 v119, v115
	v_lshl_add_u64 v[2:3], s[0:1], 0, v[2:3]
	v_lshl_add_u64 v[2:3], v[2:3], 0, v[118:119]
	v_lshlrev_b32_e32 v120, 4, v232
	v_mov_b32_e32 v121, v115
	v_lshl_add_u64 v[72:73], v[2:3], 0, v[120:121]
	global_load_dwordx4 v[82:85], v[72:73], off
	v_lshl_or_b32 v114, v4, 2, v75
	v_lshlrev_b32_e32 v4, 4, v116
	s_bfe_u32 s85, s85, 0x10006
	v_lshlrev_b64 v[2:3], 16, v[114:115]
	v_and_b32_e32 v4, 0x3f0, v4
	v_lshl_add_u64 v[2:3], s[68:69], 0, v[2:3]
	v_lshl_or_b32 v114, s85, 15, v4
	v_lshl_add_u64 v[80:81], v[2:3], 0, v[114:115]
	s_waitcnt lgkmcnt(0)
	v_lshlrev_b32_e32 v119, 2, v232
	s_mov_b64 s[0:1], 0x1000
	v_lshl_add_u64 v[200:201], v[80:81], 0, s[0:1]
	s_mov_b64 s[0:1], 0x3000
	v_lshl_add_u64 v[202:203], v[80:81], 0, s[0:1]
	s_mov_b64 s[0:1], 0x5000
	v_lshl_add_u64 v[204:205], v[80:81], 0, s[0:1]
	s_mov_b64 s[0:1], 0x7000
	v_lshl_add_u64 v[206:207], v[80:81], 0, s[0:1]
	global_load_dwordx4 v[86:89], v[72:73], off offset:32
	global_load_dwordx4 v[90:93], v[72:73], off offset:64
	global_load_dwordx4 v[94:97], v[72:73], off offset:96
	global_load_dwordx4 v[98:101], v[72:73], off offset:128
	global_load_dwordx4 v[102:105], v[72:73], off offset:160
	global_load_dwordx4 v[106:109], v[72:73], off offset:192
	global_load_dwordx4 v[110:113], v[72:73], off offset:224
	global_load_dwordx4 v[134:137], v[200:201], off offset:-4096
	global_load_dwordx4 v[138:141], v[202:203], off offset:-4096
	global_load_dwordx4 v[142:145], v[204:205], off offset:-4096
	global_load_dwordx4 v[146:149], v[206:207], off offset:-4096
	global_load_dwordx4 v[150:153], v[200:201], off offset:-3072
	global_load_dwordx4 v[154:157], v[202:203], off offset:-3072
	global_load_dwordx4 v[158:161], v[204:205], off offset:-3072
	global_load_dwordx4 v[162:165], v[206:207], off offset:-3072
	global_load_dwordx4 v[166:169], v[200:201], off offset:-2048
	global_load_dwordx4 v[170:173], v[202:203], off offset:-2048
	global_load_dwordx4 v[174:177], v[204:205], off offset:-2048
	global_load_dwordx4 v[178:181], v[206:207], off offset:-2048
	s_waitcnt vmcnt(11)
	v_mfma_f32_32x32x16_bf16 v[50:65], v[82:85], v[134:137], 0
	global_load_dwordx4 v[134:137], v[200:201], off offset:-1024
	s_waitcnt vmcnt(11)
	v_mfma_f32_32x32x16_bf16 v[34:49], v[82:85], v[138:141], 0
	global_load_dwordx4 v[138:141], v[202:203], off offset:-1024
	s_waitcnt vmcnt(11)
	v_mfma_f32_32x32x16_bf16 v[18:33], v[82:85], v[142:145], 0
	global_load_dwordx4 v[142:145], v[204:205], off offset:-1024
	s_waitcnt vmcnt(11)
	v_mfma_f32_32x32x16_bf16 v[2:17], v[82:85], v[146:149], 0
	global_load_dwordx4 v[146:149], v[206:207], off offset:-1024
	s_waitcnt vmcnt(11)
	v_mfma_f32_32x32x16_bf16 v[50:65], v[86:89], v[150:153], v[50:65]
	global_load_dwordx4 v[150:153], v[200:201], off
	s_waitcnt vmcnt(11)
	v_mfma_f32_32x32x16_bf16 v[34:49], v[86:89], v[154:157], v[34:49]
	global_load_dwordx4 v[154:157], v[202:203], off
	s_waitcnt vmcnt(11)
	v_mfma_f32_32x32x16_bf16 v[18:33], v[86:89], v[158:161], v[18:33]
	global_load_dwordx4 v[158:161], v[204:205], off
	s_waitcnt vmcnt(11)
	v_mfma_f32_32x32x16_bf16 v[2:17], v[86:89], v[162:165], v[2:17]
	global_load_dwordx4 v[162:165], v[206:207], off
	s_waitcnt vmcnt(11)
	v_mfma_f32_32x32x16_bf16 v[50:65], v[90:93], v[166:169], v[50:65]
	global_load_dwordx4 v[166:169], v[200:201], off offset:1024
	s_waitcnt vmcnt(11)
	v_mfma_f32_32x32x16_bf16 v[34:49], v[90:93], v[170:173], v[34:49]
	global_load_dwordx4 v[170:173], v[202:203], off offset:1024
	s_waitcnt vmcnt(11)
	v_mfma_f32_32x32x16_bf16 v[18:33], v[90:93], v[174:177], v[18:33]
	global_load_dwordx4 v[174:177], v[204:205], off offset:1024
	s_waitcnt vmcnt(11)
	v_mfma_f32_32x32x16_bf16 v[2:17], v[90:93], v[178:181], v[2:17]
	global_load_dwordx4 v[178:181], v[206:207], off offset:1024
	s_waitcnt vmcnt(11)
	v_mfma_f32_32x32x16_bf16 v[50:65], v[94:97], v[134:137], v[50:65]
	global_load_dwordx4 v[134:137], v[200:201], off offset:2048
	s_waitcnt vmcnt(11)
	v_mfma_f32_32x32x16_bf16 v[34:49], v[94:97], v[138:141], v[34:49]
	global_load_dwordx4 v[138:141], v[202:203], off offset:2048
	s_waitcnt vmcnt(11)
	v_mfma_f32_32x32x16_bf16 v[18:33], v[94:97], v[142:145], v[18:33]
	global_load_dwordx4 v[142:145], v[204:205], off offset:2048
	s_waitcnt vmcnt(11)
	v_mfma_f32_32x32x16_bf16 v[2:17], v[94:97], v[146:149], v[2:17]
	global_load_dwordx4 v[146:149], v[206:207], off offset:2048
	s_waitcnt vmcnt(11)
	v_mfma_f32_32x32x16_bf16 v[50:65], v[98:101], v[150:153], v[50:65]
	global_load_dwordx4 v[150:153], v[200:201], off offset:3072
	s_waitcnt vmcnt(11)
	v_mfma_f32_32x32x16_bf16 v[34:49], v[98:101], v[154:157], v[34:49]
	global_load_dwordx4 v[154:157], v[202:203], off offset:3072
	s_waitcnt vmcnt(11)
	v_mfma_f32_32x32x16_bf16 v[18:33], v[98:101], v[158:161], v[18:33]
	global_load_dwordx4 v[158:161], v[204:205], off offset:3072
	s_waitcnt vmcnt(11)
	v_mfma_f32_32x32x16_bf16 v[2:17], v[98:101], v[162:165], v[2:17]
	global_load_dwordx4 v[162:165], v[206:207], off offset:3072
	s_waitcnt vmcnt(11)
	v_mfma_f32_32x32x16_bf16 v[50:65], v[102:105], v[166:169], v[50:65]
	s_waitcnt vmcnt(10)
	v_mfma_f32_32x32x16_bf16 v[34:49], v[102:105], v[170:173], v[34:49]
	s_waitcnt vmcnt(9)
	v_mfma_f32_32x32x16_bf16 v[18:33], v[102:105], v[174:177], v[18:33]
	s_waitcnt vmcnt(8)
	v_mfma_f32_32x32x16_bf16 v[2:17], v[102:105], v[178:181], v[2:17]
	s_waitcnt vmcnt(7)
	v_mfma_f32_32x32x16_bf16 v[50:65], v[106:109], v[134:137], v[50:65]
	s_waitcnt vmcnt(6)
	v_mfma_f32_32x32x16_bf16 v[34:49], v[106:109], v[138:141], v[34:49]
	s_waitcnt vmcnt(5)
	v_mfma_f32_32x32x16_bf16 v[18:33], v[106:109], v[142:145], v[18:33]
	s_waitcnt vmcnt(4)
	v_mfma_f32_32x32x16_bf16 v[2:17], v[106:109], v[146:149], v[2:17]
	v_cmp_lt_i32_e32 vcc, -1, v74
	s_waitcnt vmcnt(3)
	v_mfma_f32_32x32x16_bf16 v[50:65], v[110:113], v[150:153], v[50:65]
	s_waitcnt vmcnt(2)
	v_mfma_f32_32x32x16_bf16 v[34:49], v[110:113], v[154:157], v[34:49]
	s_waitcnt vmcnt(1)
	v_mfma_f32_32x32x16_bf16 v[18:33], v[110:113], v[158:161], v[18:33]
	s_waitcnt vmcnt(0)
	v_mfma_f32_32x32x16_bf16 v[2:17], v[110:113], v[162:165], v[2:17]
	s_and_saveexec_b64 s[2:3], vcc
	s_cbranch_execz .LBB0_961
	s_nop 0
	s_nop 0
	s_nop 0
	s_nop 0
	s_nop 0
	s_nop 0
	s_nop 0
	s_nop 0
	v_lshlrev_b32_e32 v67, 4, v228
	v_lshlrev_b32_e32 v66, 7, v75
	v_and_b32_e32 v70, 0xffffff80, v67
	v_lshlrev_b32_e32 v67, 13, v1
	v_readlane_b32 s0, v254, 1
	v_lshlrev_b32_e32 v114, 3, v232
	v_and_b32_e32 v72, 0xc000, v67
	v_lshlrev_b32_e32 v66, 1, v66
	v_mov_b32_e32 v67, v115
	v_readlane_b32 s1, v254, 2
	v_lshlrev_b32_e32 v68, 1, v114
	v_mov_b32_e32 v69, v115
	v_lshl_add_u64 v[66:67], s[0:1], 0, v[66:67]
	v_readlane_b32 s0, v254, 3
	v_lshl_add_u64 v[122:123], v[66:67], 0, v[68:69]
	v_lshlrev_b32_e32 v66, 4, v231
	v_mov_b32_e32 v67, v115
	v_readlane_b32 s1, v254, 4
	v_lshrrev_b32_e32 v71, 3, v70
	s_lshl_b32 s34, s85, 13
	v_lshl_add_u64 v[66:67], s[0:1], 0, v[66:67]
	v_lshl_add_u64 v[124:125], v[66:67], 0, v[114:115]
	v_or_b32_e32 v66, 2, v119
	v_cmp_gt_u32_e64 s[6:7], v66, v231
	v_or_b32_e32 v66, 3, v119
	v_cmp_gt_u32_e64 s[8:9], v66, v231
	v_or_b32_e32 v66, 8, v119
	v_cmp_gt_u32_e64 s[10:11], v66, v231
	v_or_b32_e32 v66, 9, v119
	v_cmp_gt_u32_e64 s[12:13], v66, v231
	v_or_b32_e32 v66, 10, v119
	v_cmp_gt_u32_e64 s[14:15], v66, v231
	v_or_b32_e32 v66, 11, v119
	v_cmp_gt_u32_e64 s[16:17], v66, v231
	v_or_b32_e32 v66, 16, v119
	v_cmp_gt_u32_e64 s[18:19], v66, v231
	v_or_b32_e32 v66, 17, v119
	v_cmp_gt_u32_e64 s[20:21], v66, v231
	v_or_b32_e32 v66, 18, v119
	v_cmp_gt_u32_e64 s[22:23], v66, v231
	v_or_b32_e32 v66, 19, v119
	v_cmp_gt_u32_e64 s[24:25], v66, v231
	v_or_b32_e32 v66, 24, v119
	v_cmp_gt_u32_e64 s[0:1], v66, v231
	v_or_b32_e32 v66, 25, v119
	v_cmp_gt_u32_e64 s[26:27], v66, v231
	v_or_b32_e32 v66, 26, v119
	v_cmp_gt_u32_e64 s[28:29], v66, v231
	v_or_b32_e32 v66, 27, v119
	v_cmp_gt_u32_e64 s[30:31], v66, v231
	v_add3_u32 v66, v71, v72, s34
	v_cmp_gt_u32_e32 vcc, v119, v231
	v_cmp_lt_u32_e64 s[4:5], v119, v231
	v_sub_u32_e32 v121, 0, v74
	v_add_u32_e32 v126, 0x1803, v66
	v_or_b32_e32 v114, v70, v231
	s_mov_b64 s[38:39], 0
	s_branch .LBB0_958
.LBB0_957:
	s_or_b64 exec, exec, s[72:73]
	s_nop 8
	v_cvt_pk_bf16_f32 v66, v66, v67
	v_cvt_pk_bf16_f32 v67, v68, v69
	v_cvt_pk_bf16_f32 v68, v70, v71
	v_cvt_pk_bf16_f32 v69, v72, v73
	v_add_u32_e32 v121, 1, v121
	v_cmp_eq_u32_e64 s[34:35], 1, v121
	v_add_u32_e32 v114, 32, v114
	s_or_b64 s[38:39], s[34:35], s[38:39]
	v_add_u32_e32 v126, 4, v126
	s_waitcnt vmcnt(14)
	v_mfma_f32_32x32x16_bf16 v[50:65], v[66:69], v[166:169], v[50:65]
	s_waitcnt vmcnt(12)
	v_mfma_f32_32x32x16_bf16 v[34:49], v[66:69], v[170:173], v[34:49]
	s_waitcnt vmcnt(10)
	v_mfma_f32_32x32x16_bf16 v[18:33], v[66:69], v[174:177], v[18:33]
	s_waitcnt vmcnt(8)
	v_mfma_f32_32x32x16_bf16 v[2:17], v[66:69], v[178:181], v[2:17]
	v_cvt_pk_bf16_f32 v66, v74, v75
	v_cvt_pk_bf16_f32 v67, v76, v77
	v_cvt_pk_bf16_f32 v68, v78, v79
	v_cvt_pk_bf16_f32 v69, v80, v81
	s_nop 1
	s_waitcnt vmcnt(6)
	v_mfma_f32_32x32x16_bf16 v[50:65], v[66:69], v[182:185], v[50:65]
	s_waitcnt vmcnt(4)
	v_mfma_f32_32x32x16_bf16 v[34:49], v[66:69], v[186:189], v[34:49]
	s_waitcnt vmcnt(2)
	v_mfma_f32_32x32x16_bf16 v[18:33], v[66:69], v[190:193], v[18:33]
	s_waitcnt vmcnt(0)
	v_mfma_f32_32x32x16_bf16 v[2:17], v[66:69], v[194:197], v[2:17]
	s_andn2_b64 exec, exec, s[38:39]
	s_cbranch_execz .LBB0_960
.LBB0_958:
	v_lshlrev_b64 v[66:67], 10, v[114:115]
	v_lshl_add_u64 v[132:133], v[122:123], 0, v[66:67]
	global_load_dwordx4 v[134:137], v[132:133], off
	global_load_dwordx4 v[138:141], v[132:133], off offset:32
	global_load_dwordx4 v[142:145], v[132:133], off offset:64
	global_load_dwordx4 v[146:149], v[132:133], off offset:96
	global_load_dwordx4 v[150:153], v[132:133], off offset:128
	global_load_dwordx4 v[154:157], v[132:133], off offset:160
	global_load_dwordx4 v[158:161], v[132:133], off offset:192
	global_load_dwordx4 v[162:165], v[132:133], off offset:224
	v_add_u32_e32 v208, 0xffffe800, v126
	v_mov_b32_e32 v209, v115
	v_lshlrev_b64 v[208:209], 9, v[208:209]
	v_lshl_add_u64 v[208:209], v[124:125], 0, v[208:209]
	v_add_u32_e32 v210, 0xfffff000, v126
	v_mov_b32_e32 v211, v115
	v_lshlrev_b64 v[210:211], 9, v[210:211]
	v_lshl_add_u64 v[210:211], v[124:125], 0, v[210:211]
	v_add_u32_e32 v212, 0xfffff800, v126
	v_mov_b32_e32 v213, v115
	v_lshlrev_b64 v[212:213], 9, v[212:213]
	v_lshl_add_u64 v[212:213], v[124:125], 0, v[212:213]
	v_mov_b32_e32 v214, v126
	v_mov_b32_e32 v215, v115
	v_lshlrev_b64 v[214:215], 9, v[214:215]
	v_lshl_add_u64 v[214:215], v[124:125], 0, v[214:215]
	global_load_dwordx2 v[166:167], v[208:209], off offset:-1536
	global_load_dwordx2 v[168:169], v[208:209], off offset:-1024
	global_load_dwordx2 v[170:171], v[210:211], off offset:-1536
	global_load_dwordx2 v[172:173], v[210:211], off offset:-1024
	global_load_dwordx2 v[174:175], v[212:213], off offset:-1536
	global_load_dwordx2 v[176:177], v[212:213], off offset:-1024
	global_load_dwordx2 v[178:179], v[214:215], off offset:-1536
	global_load_dwordx2 v[180:181], v[214:215], off offset:-1024
	global_load_dwordx2 v[182:183], v[208:209], off offset:-512
	global_load_dwordx2 v[184:185], v[208:209], off
	global_load_dwordx2 v[186:187], v[210:211], off offset:-512
	global_load_dwordx2 v[188:189], v[210:211], off
	global_load_dwordx2 v[190:191], v[212:213], off offset:-512
	global_load_dwordx2 v[192:193], v[212:213], off
	global_load_dwordx2 v[194:195], v[214:215], off offset:-512
	global_load_dwordx2 v[196:197], v[214:215], off
	v_cmp_eq_u32_e64 s[34:35], 0, v121
	s_waitcnt vmcnt(23)
	v_mfma_f32_32x32x16_bf16 v[66:81], v[134:137], v[82:85], 0
	s_waitcnt vmcnt(22)
	v_mfma_f32_32x32x16_bf16 v[66:81], v[138:141], v[86:89], v[66:81]
	s_waitcnt vmcnt(21)
	v_mfma_f32_32x32x16_bf16 v[66:81], v[142:145], v[90:93], v[66:81]
	s_waitcnt vmcnt(20)
	v_mfma_f32_32x32x16_bf16 v[66:81], v[146:149], v[94:97], v[66:81]
	s_waitcnt vmcnt(19)
	v_mfma_f32_32x32x16_bf16 v[66:81], v[150:153], v[98:101], v[66:81]
	s_waitcnt vmcnt(18)
	v_mfma_f32_32x32x16_bf16 v[66:81], v[154:157], v[102:105], v[66:81]
	s_waitcnt vmcnt(17)
	v_mfma_f32_32x32x16_bf16 v[66:81], v[158:161], v[106:109], v[66:81]
	s_waitcnt vmcnt(16)
	v_mfma_f32_32x32x16_bf16 v[66:81], v[162:165], v[110:113], v[66:81]
	s_and_saveexec_b64 s[72:73], s[34:35]
	s_cbranch_execz .LBB0_957
	s_nop 9
	v_cndmask_b32_e64 v66, v66, 0, vcc
	v_cndmask_b32_e64 v67, 0, v67, s[4:5]
	v_cndmask_b32_e64 v68, v68, 0, s[6:7]
	v_cndmask_b32_e64 v69, v69, 0, s[8:9]
	v_cndmask_b32_e64 v70, v70, 0, s[10:11]
	v_cndmask_b32_e64 v71, v71, 0, s[12:13]
	v_cndmask_b32_e64 v72, v72, 0, s[14:15]
	v_cndmask_b32_e64 v73, v73, 0, s[16:17]
	v_cndmask_b32_e64 v74, v74, 0, s[18:19]
	v_cndmask_b32_e64 v75, v75, 0, s[20:21]
	v_cndmask_b32_e64 v76, v76, 0, s[22:23]
	v_cndmask_b32_e64 v77, v77, 0, s[24:25]
	v_cndmask_b32_e64 v78, v78, 0, s[0:1]
	v_cndmask_b32_e64 v79, v79, 0, s[26:27]
	v_cndmask_b32_e64 v80, v80, 0, s[28:29]
	v_cndmask_b32_e64 v81, v81, 0, s[30:31]
	s_branch .LBB0_957
	s_nop 0
	s_nop 0
	s_nop 0
	s_nop 0
	s_nop 0
	s_nop 0
	s_nop 0
	s_nop 0
